# v18 + first K-iteration of each tile peeled with C=0 MFMAs (accumulator zeroing removed)
# speedup vs baseline: 1.0861x; 1.0020x over previous
.LBB0_303:
	s_ashr_i32 s35, s34, 31
	s_lshl_b64 s[8:9], s[34:35], 20
	s_add_u32 s36, s53, s8
	s_addc_u32 s37, s54, s9
	s_and_b64 s[8:9], s[2:3], exec
	s_cselect_b32 s35, s37, s5
	s_cselect_b32 s52, s36, s4
	s_ashr_i32 s31, s30, 31
	s_lshl_b64 s[8:9], s[30:31], 20
	s_add_u32 s38, s55, s8
	s_addc_u32 s39, s56, s9
	s_and_b64 s[8:9], s[2:3], exec
	s_cselect_b32 s31, s39, s7
	s_cselect_b32 s77, s38, s6
	s_add_u32 s4, s4, 0x80080
	s_addc_u32 s5, s5, 0
	s_add_u32 s78, s6, 0x100
	s_addc_u32 s79, s7, 0
	s_mov_b32 s80, -2
	s_waitcnt lgkmcnt(0)
	ds_read_b128 v[2:5], v234
	ds_read_b128 v[6:9], v234 offset:1024
	ds_read_b128 v[10:13], v234 offset:2048
	ds_read_b128 v[14:17], v234 offset:3072
	ds_read_b128 v[18:21], v235
	ds_read_b128 v[22:25], v235 offset:1024
	ds_read_b128 v[26:29], v235 offset:2048
	ds_read_b128 v[30:33], v235 offset:3072
	s_add_u32 s6, s4, 0xfff80080
	s_addc_u32 s7, s5, -1
	s_cmp_eq_u32 s80, 28
	s_cselect_b32 s9, s35, s7
	s_cselect_b32 s8, s52, s6
	s_cselect_b32 s7, s31, s79
	s_cselect_b32 s6, s77, s78
	v_lshl_add_u64 v[214:215], s[4:5], 0, v[206:207]
	s_add_i32 m0, s43, 0xc000
	ds_read_b128 v[98:101], v236
	ds_read_b128 v[102:105], v236 offset:1024
	ds_read_b128 v[106:109], v236 offset:2048
	ds_read_b128 v[110:113], v236 offset:3072
	ds_read_b128 v[178:181], v236 offset:4096
	ds_read_b128 v[182:185], v236 offset:5120
	ds_read_b128 v[186:189], v236 offset:6144
	ds_read_b128 v[190:193], v236 offset:7168
	global_load_lds_dwordx4 v[214:215], off
	v_lshl_add_u64 v[214:215], s[4:5], 0, v[208:209]
	s_add_i32 m0, s43, 0xe000
	s_nop 0
	global_load_lds_dwordx4 v[214:215], off
	s_waitcnt vmcnt(8)
	s_waitcnt lgkmcnt(0)
	s_barrier
	s_waitcnt lgkmcnt(0)
	v_mfma_i32_16x16x64_i8 v[174:177], v[2:5], v[98:101], 0
	v_mfma_i32_16x16x64_i8 v[170:173], v[10:13], v[98:101], 0
	v_mfma_i32_16x16x64_i8 v[158:161], v[2:5], v[106:109], 0
	v_mfma_i32_16x16x64_i8 v[154:157], v[10:13], v[106:109], 0
	v_mfma_i32_16x16x64_i8 v[142:145], v[2:5], v[178:181], 0
	v_mfma_i32_16x16x64_i8 v[138:141], v[10:13], v[178:181], 0
	v_mfma_i32_16x16x64_i8 v[126:129], v[2:5], v[186:189], 0
	v_mfma_i32_16x16x64_i8 v[122:125], v[10:13], v[186:189], 0
	v_mfma_i32_16x16x64_i8 v[174:177], v[6:9], v[102:105], v[174:177]
	v_mfma_i32_16x16x64_i8 v[170:173], v[14:17], v[102:105], v[170:173]
	v_mfma_i32_16x16x64_i8 v[158:161], v[6:9], v[110:113], v[158:161]
	v_mfma_i32_16x16x64_i8 v[154:157], v[14:17], v[110:113], v[154:157]
	v_mfma_i32_16x16x64_i8 v[142:145], v[6:9], v[182:185], v[142:145]
	v_mfma_i32_16x16x64_i8 v[138:141], v[14:17], v[182:185], v[138:141]
	v_mfma_i32_16x16x64_i8 v[126:129], v[6:9], v[190:193], v[126:129]
	v_mfma_i32_16x16x64_i8 v[122:125], v[14:17], v[190:193], v[122:125]
	v_mfma_i32_16x16x64_i8 v[166:169], v[18:21], v[98:101], 0
	v_mfma_i32_16x16x64_i8 v[98:101], v[26:29], v[98:101], 0
	v_mfma_i32_16x16x64_i8 v[166:169], v[22:25], v[102:105], v[166:169]
	v_mfma_i32_16x16x64_i8 v[98:101], v[30:33], v[102:105], v[98:101]
	v_mfma_i32_16x16x64_i8 v[102:105], v[18:21], v[106:109], 0
	v_mfma_i32_16x16x64_i8 v[106:109], v[26:29], v[106:109], 0
	v_mfma_i32_16x16x64_i8 v[130:133], v[26:29], v[178:181], 0
	v_mfma_i32_16x16x64_i8 v[118:121], v[18:21], v[186:189], 0
	v_mfma_i32_16x16x64_i8 v[114:117], v[26:29], v[186:189], 0
	v_mfma_i32_16x16x64_i8 v[102:105], v[22:25], v[110:113], v[102:105]
	v_mfma_i32_16x16x64_i8 v[106:109], v[30:33], v[110:113], v[106:109]
	v_mfma_i32_16x16x64_i8 v[110:113], v[18:21], v[178:181], 0
	v_mfma_i32_16x16x64_i8 v[130:133], v[30:33], v[182:185], v[130:133]
	v_mfma_i32_16x16x64_i8 v[118:121], v[22:25], v[190:193], v[118:121]
	v_mfma_i32_16x16x64_i8 v[114:117], v[30:33], v[190:193], v[114:117]
	v_mfma_i32_16x16x64_i8 v[110:113], v[22:25], v[182:185], v[110:113]
	s_barrier
	s_add_i32 s81, s70, s41
	v_lshl_add_u64 v[226:227], s[6:7], 0, v[196:197]
	s_mov_b32 m0, s81
	ds_read_b128 v[134:137], v236 offset:16384
	ds_read_b128 v[146:149], v236 offset:17408
	ds_read_b128 v[150:153], v236 offset:18432
	ds_read_b128 v[162:165], v236 offset:19456
	ds_read_b128 v[178:181], v236 offset:20480
	ds_read_b128 v[182:185], v236 offset:21504
	ds_read_b128 v[186:189], v236 offset:22528
	ds_read_b128 v[190:193], v236 offset:23552
	global_load_lds_dwordx4 v[226:227], off
	s_add_i32 m0, s81, 0x2000
	s_add_u32 s82, s6, 0x80000
	v_lshl_add_u64 v[244:245], s[6:7], 0, v[198:199]
	s_addc_u32 s83, s7, 0
	s_add_i32 s81, s71, s41
	global_load_lds_dwordx4 v[244:245], off
	v_lshl_add_u64 v[214:215], s[82:83], 0, v[196:197]
	s_mov_b32 m0, s81
	v_lshl_add_u64 v[246:247], s[8:9], 0, v[196:197]
	global_load_lds_dwordx4 v[214:215], off
	v_lshl_add_u64 v[214:215], s[82:83], 0, v[198:199]
	s_add_i32 m0, s81, 0x2000
	v_lshl_add_u64 v[248:249], s[8:9], 0, v[198:199]
	global_load_lds_dwordx4 v[214:215], off
	s_mov_b32 m0, s43
	s_nop 0
	global_load_lds_dwordx4 v[246:247], off
	s_mov_b32 m0, s57
	s_nop 0
	global_load_lds_dwordx4 v[248:249], off
	s_waitcnt vmcnt(8)
	s_waitcnt lgkmcnt(0)
	s_barrier
	s_waitcnt lgkmcnt(0)
	v_mfma_i32_16x16x64_i8 v[94:97], v[2:5], v[134:137], 0
	v_mfma_i32_16x16x64_i8 v[90:93], v[10:13], v[134:137], 0
	v_mfma_i32_16x16x64_i8 v[78:81], v[2:5], v[150:153], 0
	v_mfma_i32_16x16x64_i8 v[74:77], v[10:13], v[150:153], 0
	v_mfma_i32_16x16x64_i8 v[62:65], v[2:5], v[178:181], 0
	v_mfma_i32_16x16x64_i8 v[58:61], v[10:13], v[178:181], 0
	v_mfma_i32_16x16x64_i8 v[2:5], v[2:5], v[186:189], 0
	v_mfma_i32_16x16x64_i8 v[94:97], v[6:9], v[146:149], v[94:97]
	v_mfma_i32_16x16x64_i8 v[90:93], v[14:17], v[146:149], v[90:93]
	v_mfma_i32_16x16x64_i8 v[78:81], v[6:9], v[162:165], v[78:81]
	v_mfma_i32_16x16x64_i8 v[74:77], v[14:17], v[162:165], v[74:77]
	v_mfma_i32_16x16x64_i8 v[62:65], v[6:9], v[182:185], v[62:65]
	v_mfma_i32_16x16x64_i8 v[58:61], v[14:17], v[182:185], v[58:61]
	v_mfma_i32_16x16x64_i8 v[2:5], v[6:9], v[190:193], v[2:5]
	v_mfma_i32_16x16x64_i8 v[6:9], v[10:13], v[186:189], 0
	v_mfma_i32_16x16x64_i8 v[6:9], v[14:17], v[190:193], v[6:9]
	v_mfma_i32_16x16x64_i8 v[42:45], v[18:21], v[150:153], 0
	v_mfma_i32_16x16x64_i8 v[70:73], v[22:25], v[162:165], v[42:45]
	v_mfma_i32_16x16x64_i8 v[42:45], v[26:29], v[150:153], 0
	v_mfma_i32_16x16x64_i8 v[66:69], v[30:33], v[162:165], v[42:45]
	v_mfma_i32_16x16x64_i8 v[42:45], v[18:21], v[178:181], 0
	v_mfma_i32_16x16x64_i8 v[10:13], v[18:21], v[134:137], 0
	v_mfma_i32_16x16x64_i8 v[54:57], v[22:25], v[182:185], v[42:45]
	v_mfma_i32_16x16x64_i8 v[42:45], v[26:29], v[178:181], 0
	v_mfma_i32_16x16x64_i8 v[18:21], v[18:21], v[186:189], 0
	v_mfma_i32_16x16x64_i8 v[10:13], v[22:25], v[146:149], v[10:13]
	v_mfma_i32_16x16x64_i8 v[14:17], v[26:29], v[134:137], 0
	v_mfma_i32_16x16x64_i8 v[50:53], v[30:33], v[182:185], v[42:45]
	v_mfma_i32_16x16x64_i8 v[18:21], v[22:25], v[190:193], v[18:21]
	v_mfma_i32_16x16x64_i8 v[22:25], v[26:29], v[186:189], 0
	v_mfma_i32_16x16x64_i8 v[14:17], v[30:33], v[146:149], v[14:17]
	v_mfma_i32_16x16x64_i8 v[22:25], v[30:33], v[190:193], v[22:25]
	s_barrier
	s_add_i32 s81, 0, 0x18000
	s_add_i32 s82, 0, 0x1c000
	v_add_u32_e32 v38, s81, v229
	v_add_u32_e32 v42, s82, v229
	ds_read_b128 v[26:29], v38
	ds_read_b128 v[30:33], v38 offset:1024
	ds_read_b128 v[34:37], v38 offset:2048
	ds_read_b128 v[38:41], v38 offset:3072
	ds_read_b128 v[178:181], v42
	ds_read_b128 v[182:185], v42 offset:1024
	ds_read_b128 v[186:189], v42 offset:2048
	ds_read_b128 v[190:193], v42 offset:3072
	s_add_u32 s8, s8, 0x80000
	s_addc_u32 s9, s9, 0
	s_mov_b32 m0, s60
	v_lshl_add_u64 v[134:135], s[8:9], 0, v[196:197]
	ds_read_b128 v[42:45], v236 offset:32768
	ds_read_b128 v[46:49], v236 offset:33792
	ds_read_b128 v[82:85], v236 offset:34816
	ds_read_b128 v[86:89], v236 offset:35840
	ds_read_b128 v[214:217], v236 offset:36864
	ds_read_b128 v[218:221], v236 offset:37888
	ds_read_b128 v[222:225], v236 offset:38912
	ds_read_b128 v[240:243], v236 offset:39936
	global_load_lds_dwordx4 v[134:135], off
	v_lshl_add_u64 v[134:135], s[8:9], 0, v[198:199]
	s_mov_b32 m0, s61
	s_nop 0
	global_load_lds_dwordx4 v[134:135], off
	s_waitcnt vmcnt(8)
	s_waitcnt lgkmcnt(0)
	s_barrier
	s_waitcnt lgkmcnt(0)
	v_mfma_i32_16x16x64_i8 v[134:137], v[26:29], v[42:45], v[174:177]
	v_mfma_i32_16x16x64_i8 v[174:177], v[30:33], v[46:49], v[134:137]
	v_mfma_i32_16x16x64_i8 v[134:137], v[34:37], v[42:45], v[170:173]
	v_mfma_i32_16x16x64_i8 v[170:173], v[38:41], v[46:49], v[134:137]
	v_mfma_i32_16x16x64_i8 v[134:137], v[26:29], v[82:85], v[158:161]
	v_mfma_i32_16x16x64_i8 v[158:161], v[30:33], v[86:89], v[134:137]
	v_mfma_i32_16x16x64_i8 v[134:137], v[34:37], v[82:85], v[154:157]
	v_mfma_i32_16x16x64_i8 v[154:157], v[38:41], v[86:89], v[134:137]
	v_mfma_i32_16x16x64_i8 v[134:137], v[26:29], v[214:217], v[142:145]
	v_mfma_i32_16x16x64_i8 v[142:145], v[30:33], v[218:221], v[134:137]
	v_mfma_i32_16x16x64_i8 v[134:137], v[34:37], v[214:217], v[138:141]
	v_mfma_i32_16x16x64_i8 v[126:129], v[26:29], v[222:225], v[126:129]
	v_mfma_i32_16x16x64_i8 v[122:125], v[34:37], v[222:225], v[122:125]
	v_mfma_i32_16x16x64_i8 v[138:141], v[38:41], v[218:221], v[134:137]
	v_mfma_i32_16x16x64_i8 v[126:129], v[30:33], v[240:243], v[126:129]
	v_mfma_i32_16x16x64_i8 v[122:125], v[38:41], v[240:243], v[122:125]
	v_mfma_i32_16x16x64_i8 v[134:137], v[178:181], v[42:45], v[166:169]
	v_mfma_i32_16x16x64_i8 v[42:45], v[186:189], v[42:45], v[98:101]
	v_mfma_i32_16x16x64_i8 v[162:165], v[190:193], v[46:49], v[42:45]
	v_mfma_i32_16x16x64_i8 v[42:45], v[178:181], v[82:85], v[102:105]
	v_mfma_i32_16x16x64_i8 v[150:153], v[182:185], v[86:89], v[42:45]
	v_mfma_i32_16x16x64_i8 v[42:45], v[186:189], v[82:85], v[106:109]
	v_mfma_i32_16x16x64_i8 v[146:149], v[190:193], v[86:89], v[42:45]
	v_mfma_i32_16x16x64_i8 v[42:45], v[178:181], v[214:217], v[110:113]
	v_mfma_i32_16x16x64_i8 v[166:169], v[182:185], v[46:49], v[134:137]
	v_mfma_i32_16x16x64_i8 v[134:137], v[182:185], v[218:221], v[42:45]
	v_mfma_i32_16x16x64_i8 v[42:45], v[186:189], v[214:217], v[130:133]
	v_mfma_i32_16x16x64_i8 v[130:133], v[190:193], v[218:221], v[42:45]
	v_mfma_i32_16x16x64_i8 v[42:45], v[178:181], v[222:225], v[118:121]
	v_mfma_i32_16x16x64_i8 v[118:121], v[182:185], v[240:243], v[42:45]
	v_mfma_i32_16x16x64_i8 v[42:45], v[186:189], v[222:225], v[114:117]
	v_mfma_i32_16x16x64_i8 v[114:117], v[190:193], v[240:243], v[42:45]
	s_barrier
	s_add_i32 s8, s81, s41
	s_nop 3
	v_lshl_add_u64 v[42:43], v[226:227], 0, s[24:25]
	s_mov_b32 m0, s8
	ds_read_b128 v[82:85], v236 offset:49152
	ds_read_b128 v[98:101], v236 offset:50176
	ds_read_b128 v[102:105], v236 offset:51200
	ds_read_b128 v[106:109], v236 offset:52224
	ds_read_b128 v[110:113], v236 offset:53248
	ds_read_b128 v[214:217], v236 offset:54272
	ds_read_b128 v[218:221], v236 offset:55296
	ds_read_b128 v[222:225], v236 offset:56320
	global_load_lds_dwordx4 v[42:43], off
	s_add_i32 m0, s8, 0x2000
	s_add_u32 s6, s6, 0x80080
	v_lshl_add_u64 v[42:43], v[244:245], 0, s[24:25]
	s_addc_u32 s7, s7, 0
	s_add_i32 s8, s82, s41
	global_load_lds_dwordx4 v[42:43], off
	v_lshl_add_u64 v[42:43], s[6:7], 0, v[196:197]
	s_mov_b32 m0, s8
	s_nop 0
	global_load_lds_dwordx4 v[42:43], off
	v_lshl_add_u64 v[42:43], s[6:7], 0, v[198:199]
	s_add_i32 m0, s8, 0x2000
	s_nop 0
	global_load_lds_dwordx4 v[42:43], off
	v_lshl_add_u64 v[42:43], v[246:247], 0, s[24:25]
	s_mov_b32 m0, s63
	s_nop 0
	global_load_lds_dwordx4 v[42:43], off
	v_lshl_add_u64 v[42:43], v[248:249], 0, s[24:25]
	s_mov_b32 m0, s64
	s_nop 0
	global_load_lds_dwordx4 v[42:43], off
	s_waitcnt vmcnt(8)
	s_waitcnt lgkmcnt(0)
	s_barrier
	s_waitcnt lgkmcnt(0)
	v_mfma_i32_16x16x64_i8 v[42:45], v[26:29], v[82:85], v[94:97]
	v_mfma_i32_16x16x64_i8 v[94:97], v[30:33], v[98:101], v[42:45]
	v_mfma_i32_16x16x64_i8 v[42:45], v[34:37], v[82:85], v[90:93]
	v_mfma_i32_16x16x64_i8 v[90:93], v[38:41], v[98:101], v[42:45]
	v_mfma_i32_16x16x64_i8 v[42:45], v[26:29], v[102:105], v[78:81]
	v_mfma_i32_16x16x64_i8 v[78:81], v[30:33], v[106:109], v[42:45]
	v_mfma_i32_16x16x64_i8 v[42:45], v[34:37], v[102:105], v[74:77]
	v_mfma_i32_16x16x64_i8 v[74:77], v[38:41], v[106:109], v[42:45]
	v_mfma_i32_16x16x64_i8 v[42:45], v[26:29], v[110:113], v[62:65]
	v_mfma_i32_16x16x64_i8 v[2:5], v[26:29], v[218:221], v[2:5]
	v_mfma_i32_16x16x64_i8 v[62:65], v[30:33], v[214:217], v[42:45]
	v_mfma_i32_16x16x64_i8 v[42:45], v[34:37], v[110:113], v[58:61]
	v_mfma_i32_16x16x64_i8 v[46:49], v[30:33], v[222:225], v[2:5]
	v_mfma_i32_16x16x64_i8 v[2:5], v[34:37], v[218:221], v[6:9]
	v_mfma_i32_16x16x64_i8 v[58:61], v[38:41], v[214:217], v[42:45]
	v_mfma_i32_16x16x64_i8 v[42:45], v[38:41], v[222:225], v[2:5]
	v_mfma_i32_16x16x64_i8 v[2:5], v[178:181], v[82:85], v[10:13]
	v_mfma_i32_16x16x64_i8 v[86:89], v[182:185], v[98:101], v[2:5]
	v_mfma_i32_16x16x64_i8 v[2:5], v[186:189], v[82:85], v[14:17]
	v_mfma_i32_16x16x64_i8 v[82:85], v[190:193], v[98:101], v[2:5]
	v_mfma_i32_16x16x64_i8 v[2:5], v[178:181], v[102:105], v[70:73]
	v_mfma_i32_16x16x64_i8 v[70:73], v[182:185], v[106:109], v[2:5]
	v_mfma_i32_16x16x64_i8 v[2:5], v[186:189], v[102:105], v[66:69]
	v_mfma_i32_16x16x64_i8 v[66:69], v[190:193], v[106:109], v[2:5]
	v_mfma_i32_16x16x64_i8 v[2:5], v[178:181], v[110:113], v[54:57]
	v_mfma_i32_16x16x64_i8 v[54:57], v[182:185], v[214:217], v[2:5]
	v_mfma_i32_16x16x64_i8 v[2:5], v[186:189], v[110:113], v[50:53]
	v_mfma_i32_16x16x64_i8 v[50:53], v[190:193], v[214:217], v[2:5]
	v_mfma_i32_16x16x64_i8 v[2:5], v[178:181], v[218:221], v[18:21]
	v_mfma_i32_16x16x64_i8 v[38:41], v[182:185], v[222:225], v[2:5]
	v_mfma_i32_16x16x64_i8 v[2:5], v[186:189], v[218:221], v[22:25]
	v_mfma_i32_16x16x64_i8 v[34:37], v[190:193], v[222:225], v[2:5]
	s_barrier
	s_add_i32 s80, s80, 2
	s_add_u32 s4, s4, 0x100
	s_addc_u32 s5, s5, 0
	s_add_u32 s78, s78, 0x100
	s_addc_u32 s79, s79, 0
	s_cmp_gt_u32 s80, 29

.LBB0_1231:
	s_ashr_i32 s23, s22, 31
	s_lshl_b64 s[24:25], s[22:23], 20
	s_add_u32 s24, s17, s24
	s_addc_u32 s25, s36, s25
	s_and_b64 s[26:27], s[0:1], exec
	s_cselect_b32 s23, s25, s29
	s_cselect_b32 s66, s24, s28
	s_ashr_i32 s15, s14, 31
	s_lshl_b64 s[26:27], s[14:15], 20
	s_add_u32 s26, s37, s26
	s_addc_u32 s27, s38, s27
	s_and_b64 s[34:35], s[0:1], exec
	s_cselect_b32 s15, s27, s31
	s_cselect_b32 s67, s26, s30
	s_add_u32 s28, s28, 0x80080
	s_addc_u32 s29, s29, 0
	s_add_u32 s68, s30, 0x100
	s_addc_u32 s69, s31, 0
	s_mov_b32 s70, -2
	ds_read_b128 v[106:109], v197
	ds_read_b128 v[114:117], v197 offset:1024
	ds_read_b128 v[122:125], v197 offset:2048
	ds_read_b128 v[130:133], v197 offset:3072
	ds_read_b128 v[146:149], v201
	ds_read_b128 v[150:153], v201 offset:1024
	ds_read_b128 v[154:157], v201 offset:2048
	ds_read_b128 v[158:161], v201 offset:3072
	s_add_u32 s30, s28, 0xfff80080
	s_addc_u32 s31, s29, -1
	s_cmp_eq_u32 s70, 28
	s_cselect_b32 s35, s23, s31
	s_cselect_b32 s34, s66, s30
	s_cselect_b32 s31, s15, s69
	s_cselect_b32 s30, s67, s68
	v_lshl_add_u64 v[194:195], s[28:29], 0, v[174:175]
	s_add_i32 m0, s19, 0xc000
	ds_read_b128 v[162:165], v204
	ds_read_b128 v[182:185], v204 offset:1024
	ds_read_b128 v[186:189], v204 offset:2048
	ds_read_b128 v[206:209], v204 offset:3072
	ds_read_b128 v[210:213], v204 offset:4096
	ds_read_b128 v[214:217], v204 offset:5120
	ds_read_b128 v[218:221], v204 offset:6144
	ds_read_b128 v[222:225], v204 offset:7168
	global_load_lds_dwordx4 v[194:195], off
	v_lshl_add_u64 v[194:195], s[28:29], 0, v[176:177]
	s_add_i32 m0, s19, 0xe000
	s_nop 0
	global_load_lds_dwordx4 v[194:195], off
	s_waitcnt vmcnt(8)
	s_waitcnt lgkmcnt(0)
	s_barrier
	s_waitcnt lgkmcnt(0)
	v_mfma_i32_16x16x64_i8 v[142:145], v[106:109], v[162:165], 0
	v_mfma_i32_16x16x64_i8 v[138:141], v[122:125], v[162:165], 0
	v_mfma_i32_16x16x64_i8 v[118:121], v[106:109], v[186:189], 0
	v_mfma_i32_16x16x64_i8 v[110:113], v[122:125], v[186:189], 0
	v_mfma_i32_16x16x64_i8 v[94:97], v[106:109], v[210:213], 0
	v_mfma_i32_16x16x64_i8 v[90:93], v[122:125], v[210:213], 0
	v_mfma_i32_16x16x64_i8 v[78:81], v[106:109], v[218:221], 0
	v_mfma_i32_16x16x64_i8 v[74:77], v[122:125], v[218:221], 0
	v_mfma_i32_16x16x64_i8 v[142:145], v[114:117], v[182:185], v[142:145]
	v_mfma_i32_16x16x64_i8 v[138:141], v[130:133], v[182:185], v[138:141]
	v_mfma_i32_16x16x64_i8 v[118:121], v[114:117], v[206:209], v[118:121]
	v_mfma_i32_16x16x64_i8 v[110:113], v[130:133], v[206:209], v[110:113]
	v_mfma_i32_16x16x64_i8 v[94:97], v[114:117], v[214:217], v[94:97]
	v_mfma_i32_16x16x64_i8 v[90:93], v[130:133], v[214:217], v[90:93]
	v_mfma_i32_16x16x64_i8 v[78:81], v[114:117], v[222:225], v[78:81]
	v_mfma_i32_16x16x64_i8 v[74:77], v[130:133], v[222:225], v[74:77]
	v_mfma_i32_16x16x64_i8 v[134:137], v[146:149], v[162:165], 0
	v_mfma_i32_16x16x64_i8 v[126:129], v[154:157], v[162:165], 0
	v_mfma_i32_16x16x64_i8 v[102:105], v[146:149], v[186:189], 0
	v_mfma_i32_16x16x64_i8 v[98:101], v[154:157], v[186:189], 0
	v_mfma_i32_16x16x64_i8 v[86:89], v[146:149], v[210:213], 0
	v_mfma_i32_16x16x64_i8 v[82:85], v[154:157], v[210:213], 0
	v_mfma_i32_16x16x64_i8 v[70:73], v[146:149], v[218:221], 0
	v_mfma_i32_16x16x64_i8 v[66:69], v[154:157], v[218:221], 0
	v_mfma_i32_16x16x64_i8 v[134:137], v[150:153], v[182:185], v[134:137]
	v_mfma_i32_16x16x64_i8 v[126:129], v[158:161], v[182:185], v[126:129]
	v_mfma_i32_16x16x64_i8 v[102:105], v[150:153], v[206:209], v[102:105]
	v_mfma_i32_16x16x64_i8 v[98:101], v[158:161], v[206:209], v[98:101]
	v_mfma_i32_16x16x64_i8 v[86:89], v[150:153], v[214:217], v[86:89]
	v_mfma_i32_16x16x64_i8 v[82:85], v[158:161], v[214:217], v[82:85]
	v_mfma_i32_16x16x64_i8 v[70:73], v[150:153], v[222:225], v[70:73]
	v_mfma_i32_16x16x64_i8 v[66:69], v[158:161], v[222:225], v[66:69]
	s_barrier
	s_add_i32 s71, s63, s39
	v_lshl_add_u64 v[194:195], s[30:31], 0, v[168:169]
	s_mov_b32 m0, s71
	ds_read_b128 v[162:165], v204 offset:16384
	ds_read_b128 v[182:185], v204 offset:17408
	ds_read_b128 v[186:189], v204 offset:18432
	ds_read_b128 v[206:209], v204 offset:19456
	ds_read_b128 v[210:213], v204 offset:20480
	ds_read_b128 v[214:217], v204 offset:21504
	ds_read_b128 v[218:221], v204 offset:22528
	ds_read_b128 v[222:225], v204 offset:23552
	global_load_lds_dwordx4 v[194:195], off
	s_add_i32 m0, s71, 0x2000
	s_add_u32 s72, s30, 0x80000
	v_lshl_add_u64 v[198:199], s[30:31], 0, v[172:173]
	s_addc_u32 s73, s31, 0
	s_add_i32 s71, s64, s39
	global_load_lds_dwordx4 v[198:199], off
	v_lshl_add_u64 v[202:203], s[72:73], 0, v[168:169]
	s_mov_b32 m0, s71
	v_lshl_add_u64 v[226:227], s[34:35], 0, v[170:171]
	global_load_lds_dwordx4 v[202:203], off
	v_lshl_add_u64 v[202:203], s[72:73], 0, v[172:173]
	s_add_i32 m0, s71, 0x2000
	s_nop 0
	global_load_lds_dwordx4 v[202:203], off
	v_lshl_add_u64 v[202:203], s[34:35], 0, v[166:167]
	s_mov_b32 m0, s19
	s_nop 0
	global_load_lds_dwordx4 v[202:203], off
	s_mov_b32 m0, s40
	s_nop 0
	global_load_lds_dwordx4 v[226:227], off
	s_waitcnt vmcnt(8)
	s_waitcnt lgkmcnt(0)
	s_barrier
	s_waitcnt lgkmcnt(0)
	v_mfma_i32_16x16x64_i8 v[62:65], v[106:109], v[162:165], 0
	v_mfma_i32_16x16x64_i8 v[58:61], v[122:125], v[162:165], 0
	v_mfma_i32_16x16x64_i8 v[46:49], v[106:109], v[186:189], 0
	v_mfma_i32_16x16x64_i8 v[42:45], v[122:125], v[186:189], 0
	v_mfma_i32_16x16x64_i8 v[30:33], v[106:109], v[210:213], 0
	v_mfma_i32_16x16x64_i8 v[26:29], v[122:125], v[210:213], 0
	v_mfma_i32_16x16x64_i8 v[14:17], v[106:109], v[218:221], 0
	v_mfma_i32_16x16x64_i8 v[10:13], v[122:125], v[218:221], 0
	v_mfma_i32_16x16x64_i8 v[62:65], v[114:117], v[182:185], v[62:65]
	v_mfma_i32_16x16x64_i8 v[58:61], v[130:133], v[182:185], v[58:61]
	v_mfma_i32_16x16x64_i8 v[46:49], v[114:117], v[206:209], v[46:49]
	v_mfma_i32_16x16x64_i8 v[42:45], v[130:133], v[206:209], v[42:45]
	v_mfma_i32_16x16x64_i8 v[30:33], v[114:117], v[214:217], v[30:33]
	v_mfma_i32_16x16x64_i8 v[26:29], v[130:133], v[214:217], v[26:29]
	v_mfma_i32_16x16x64_i8 v[14:17], v[114:117], v[222:225], v[14:17]
	v_mfma_i32_16x16x64_i8 v[10:13], v[130:133], v[222:225], v[10:13]
	v_mfma_i32_16x16x64_i8 v[54:57], v[146:149], v[162:165], 0
	v_mfma_i32_16x16x64_i8 v[50:53], v[154:157], v[162:165], 0
	v_mfma_i32_16x16x64_i8 v[38:41], v[146:149], v[186:189], 0
	v_mfma_i32_16x16x64_i8 v[34:37], v[154:157], v[186:189], 0
	v_mfma_i32_16x16x64_i8 v[22:25], v[146:149], v[210:213], 0
	v_mfma_i32_16x16x64_i8 v[18:21], v[154:157], v[210:213], 0
	v_mfma_i32_16x16x64_i8 v[6:9], v[146:149], v[218:221], 0
	v_mfma_i32_16x16x64_i8 v[2:5], v[154:157], v[218:221], 0
	v_mfma_i32_16x16x64_i8 v[54:57], v[150:153], v[182:185], v[54:57]
	v_mfma_i32_16x16x64_i8 v[50:53], v[158:161], v[182:185], v[50:53]
	v_mfma_i32_16x16x64_i8 v[38:41], v[150:153], v[206:209], v[38:41]
	v_mfma_i32_16x16x64_i8 v[34:37], v[158:161], v[206:209], v[34:37]
	v_mfma_i32_16x16x64_i8 v[22:25], v[150:153], v[214:217], v[22:25]
	v_mfma_i32_16x16x64_i8 v[18:21], v[158:161], v[214:217], v[18:21]
	v_mfma_i32_16x16x64_i8 v[6:9], v[150:153], v[222:225], v[6:9]
	v_mfma_i32_16x16x64_i8 v[2:5], v[158:161], v[222:225], v[2:5]
	s_barrier
	s_add_i32 s71, 0, 0x18000
	s_add_i32 s72, 0, 0x1c000
	v_add_u32_e32 v130, s71, v193
	v_add_u32_e32 v158, s72, v193
	ds_read_b128 v[106:109], v130
	ds_read_b128 v[114:117], v130 offset:1024
	ds_read_b128 v[122:125], v130 offset:2048
	ds_read_b128 v[130:133], v130 offset:3072
	ds_read_b128 v[146:149], v158
	ds_read_b128 v[150:153], v158 offset:1024
	ds_read_b128 v[154:157], v158 offset:2048
	ds_read_b128 v[158:161], v158 offset:3072
	s_add_u32 s34, s34, 0x80000
	s_addc_u32 s35, s35, 0
	s_mov_b32 m0, s41
	v_lshl_add_u64 v[228:229], s[34:35], 0, v[166:167]
	ds_read_b128 v[162:165], v204 offset:32768
	ds_read_b128 v[182:185], v204 offset:33792
	ds_read_b128 v[186:189], v204 offset:34816
	ds_read_b128 v[206:209], v204 offset:35840
	ds_read_b128 v[210:213], v204 offset:36864
	ds_read_b128 v[214:217], v204 offset:37888
	ds_read_b128 v[218:221], v204 offset:38912
	ds_read_b128 v[222:225], v204 offset:39936
	global_load_lds_dwordx4 v[228:229], off
	v_lshl_add_u64 v[228:229], s[34:35], 0, v[170:171]
	s_mov_b32 m0, s42
	s_nop 0
	global_load_lds_dwordx4 v[228:229], off
	s_waitcnt vmcnt(8)
	s_waitcnt lgkmcnt(0)
	s_barrier
	s_waitcnt lgkmcnt(0)
	v_mfma_i32_16x16x64_i8 v[142:145], v[106:109], v[162:165], v[142:145]
	v_mfma_i32_16x16x64_i8 v[138:141], v[122:125], v[162:165], v[138:141]
	v_mfma_i32_16x16x64_i8 v[118:121], v[106:109], v[186:189], v[118:121]
	v_mfma_i32_16x16x64_i8 v[110:113], v[122:125], v[186:189], v[110:113]
	v_mfma_i32_16x16x64_i8 v[94:97], v[106:109], v[210:213], v[94:97]
	v_mfma_i32_16x16x64_i8 v[90:93], v[122:125], v[210:213], v[90:93]
	v_mfma_i32_16x16x64_i8 v[78:81], v[106:109], v[218:221], v[78:81]
	v_mfma_i32_16x16x64_i8 v[74:77], v[122:125], v[218:221], v[74:77]
	v_mfma_i32_16x16x64_i8 v[142:145], v[114:117], v[182:185], v[142:145]
	v_mfma_i32_16x16x64_i8 v[138:141], v[130:133], v[182:185], v[138:141]
	v_mfma_i32_16x16x64_i8 v[118:121], v[114:117], v[206:209], v[118:121]
	v_mfma_i32_16x16x64_i8 v[110:113], v[130:133], v[206:209], v[110:113]
	v_mfma_i32_16x16x64_i8 v[94:97], v[114:117], v[214:217], v[94:97]
	v_mfma_i32_16x16x64_i8 v[90:93], v[130:133], v[214:217], v[90:93]
	v_mfma_i32_16x16x64_i8 v[78:81], v[114:117], v[222:225], v[78:81]
	v_mfma_i32_16x16x64_i8 v[74:77], v[130:133], v[222:225], v[74:77]
	v_mfma_i32_16x16x64_i8 v[134:137], v[146:149], v[162:165], v[134:137]
	v_mfma_i32_16x16x64_i8 v[126:129], v[154:157], v[162:165], v[126:129]
	v_mfma_i32_16x16x64_i8 v[102:105], v[146:149], v[186:189], v[102:105]
	v_mfma_i32_16x16x64_i8 v[98:101], v[154:157], v[186:189], v[98:101]
	v_mfma_i32_16x16x64_i8 v[86:89], v[146:149], v[210:213], v[86:89]
	v_mfma_i32_16x16x64_i8 v[82:85], v[154:157], v[210:213], v[82:85]
	v_mfma_i32_16x16x64_i8 v[70:73], v[146:149], v[218:221], v[70:73]
	v_mfma_i32_16x16x64_i8 v[66:69], v[154:157], v[218:221], v[66:69]
	v_mfma_i32_16x16x64_i8 v[134:137], v[150:153], v[182:185], v[134:137]
	v_mfma_i32_16x16x64_i8 v[126:129], v[158:161], v[182:185], v[126:129]
	v_mfma_i32_16x16x64_i8 v[102:105], v[150:153], v[206:209], v[102:105]
	v_mfma_i32_16x16x64_i8 v[98:101], v[158:161], v[206:209], v[98:101]
	v_mfma_i32_16x16x64_i8 v[86:89], v[150:153], v[214:217], v[86:89]
	v_mfma_i32_16x16x64_i8 v[82:85], v[158:161], v[214:217], v[82:85]
	v_mfma_i32_16x16x64_i8 v[70:73], v[150:153], v[222:225], v[70:73]
	v_mfma_i32_16x16x64_i8 v[66:69], v[158:161], v[222:225], v[66:69]
	s_barrier
	s_add_i32 s34, s71, s39
	v_lshl_add_u64 v[194:195], v[194:195], 0, s[10:11]
	s_mov_b32 m0, s34
	ds_read_b128 v[162:165], v204 offset:49152
	ds_read_b128 v[182:185], v204 offset:50176
	ds_read_b128 v[186:189], v204 offset:51200
	ds_read_b128 v[206:209], v204 offset:52224
	ds_read_b128 v[210:213], v204 offset:53248
	ds_read_b128 v[214:217], v204 offset:54272
	ds_read_b128 v[218:221], v204 offset:55296
	ds_read_b128 v[222:225], v204 offset:56320
	global_load_lds_dwordx4 v[194:195], off
	s_add_i32 m0, s34, 0x2000
	s_add_u32 s30, s30, 0x80080
	v_lshl_add_u64 v[194:195], v[198:199], 0, s[10:11]
	s_addc_u32 s31, s31, 0
	s_add_i32 s34, s72, s39
	global_load_lds_dwordx4 v[194:195], off
	v_lshl_add_u64 v[194:195], s[30:31], 0, v[168:169]
	s_mov_b32 m0, s34
	s_nop 0
	global_load_lds_dwordx4 v[194:195], off
	v_lshl_add_u64 v[194:195], s[30:31], 0, v[172:173]
	s_add_i32 m0, s34, 0x2000
	s_nop 0
	global_load_lds_dwordx4 v[194:195], off
	v_lshl_add_u64 v[194:195], v[202:203], 0, s[10:11]
	s_mov_b32 m0, s60
	s_nop 0
	global_load_lds_dwordx4 v[194:195], off
	v_lshl_add_u64 v[194:195], v[226:227], 0, s[10:11]
	s_mov_b32 m0, s61
	s_nop 0
	global_load_lds_dwordx4 v[194:195], off
	s_waitcnt vmcnt(8)
	s_waitcnt lgkmcnt(0)
	s_barrier
	s_waitcnt lgkmcnt(0)
	v_mfma_i32_16x16x64_i8 v[62:65], v[106:109], v[162:165], v[62:65]
	v_mfma_i32_16x16x64_i8 v[58:61], v[122:125], v[162:165], v[58:61]
	v_mfma_i32_16x16x64_i8 v[46:49], v[106:109], v[186:189], v[46:49]
	v_mfma_i32_16x16x64_i8 v[42:45], v[122:125], v[186:189], v[42:45]
	v_mfma_i32_16x16x64_i8 v[30:33], v[106:109], v[210:213], v[30:33]
	v_mfma_i32_16x16x64_i8 v[26:29], v[122:125], v[210:213], v[26:29]
	v_mfma_i32_16x16x64_i8 v[14:17], v[106:109], v[218:221], v[14:17]
	v_mfma_i32_16x16x64_i8 v[10:13], v[122:125], v[218:221], v[10:13]
	v_mfma_i32_16x16x64_i8 v[62:65], v[114:117], v[182:185], v[62:65]
	v_mfma_i32_16x16x64_i8 v[58:61], v[130:133], v[182:185], v[58:61]
	v_mfma_i32_16x16x64_i8 v[46:49], v[114:117], v[206:209], v[46:49]
	v_mfma_i32_16x16x64_i8 v[42:45], v[130:133], v[206:209], v[42:45]
	v_mfma_i32_16x16x64_i8 v[30:33], v[114:117], v[214:217], v[30:33]
	v_mfma_i32_16x16x64_i8 v[26:29], v[130:133], v[214:217], v[26:29]
	v_mfma_i32_16x16x64_i8 v[14:17], v[114:117], v[222:225], v[14:17]
	v_mfma_i32_16x16x64_i8 v[10:13], v[130:133], v[222:225], v[10:13]
	v_mfma_i32_16x16x64_i8 v[54:57], v[146:149], v[162:165], v[54:57]
	v_mfma_i32_16x16x64_i8 v[50:53], v[154:157], v[162:165], v[50:53]
	v_mfma_i32_16x16x64_i8 v[38:41], v[146:149], v[186:189], v[38:41]
	v_mfma_i32_16x16x64_i8 v[34:37], v[154:157], v[186:189], v[34:37]
	v_mfma_i32_16x16x64_i8 v[22:25], v[146:149], v[210:213], v[22:25]
	v_mfma_i32_16x16x64_i8 v[18:21], v[154:157], v[210:213], v[18:21]
	v_mfma_i32_16x16x64_i8 v[6:9], v[146:149], v[218:221], v[6:9]
	v_mfma_i32_16x16x64_i8 v[2:5], v[154:157], v[218:221], v[2:5]
	v_mfma_i32_16x16x64_i8 v[54:57], v[150:153], v[182:185], v[54:57]
	v_mfma_i32_16x16x64_i8 v[50:53], v[158:161], v[182:185], v[50:53]
	v_mfma_i32_16x16x64_i8 v[38:41], v[150:153], v[206:209], v[38:41]
	v_mfma_i32_16x16x64_i8 v[34:37], v[158:161], v[206:209], v[34:37]
	v_mfma_i32_16x16x64_i8 v[22:25], v[150:153], v[214:217], v[22:25]
	v_mfma_i32_16x16x64_i8 v[18:21], v[158:161], v[214:217], v[18:21]
	v_mfma_i32_16x16x64_i8 v[6:9], v[150:153], v[222:225], v[6:9]
	v_mfma_i32_16x16x64_i8 v[2:5], v[158:161], v[222:225], v[2:5]
	s_barrier
	s_add_i32 s70, s70, 2
	s_add_u32 s28, s28, 0x100
	s_addc_u32 s29, s29, 0
	s_add_u32 s68, s68, 0x100
	s_addc_u32 s69, s69, 0
	s_cmp_gt_u32 s70, 29

.LBB0_1366:
	s_ashr_i32 s35, s34, 31
	s_lshl_b64 s[18:19], s[34:35], 20
	s_add_u32 s36, s29, s18
	s_addc_u32 s37, s60, s19
	s_and_b64 s[18:19], s[2:3], exec
	s_cselect_b32 s35, s37, s5
	s_cselect_b32 s43, s36, s4
	s_ashr_i32 s31, s30, 31
	s_lshl_b64 s[18:19], s[30:31], 20
	s_add_u32 s38, s61, s18
	s_addc_u32 s39, s62, s19
	s_and_b64 s[18:19], s[2:3], exec
	s_cselect_b32 s31, s39, s7
	s_cselect_b32 vcc_lo, s38, s6
	s_add_u32 vcc_hi, s6, 0x100
	s_addc_u32 s79, s7, 0
	s_mov_b32 s80, -2
	ds_read_b128 v[130:133], v234
	ds_read_b128 v[134:137], v234 offset:1024
	ds_read_b128 v[162:165], v234 offset:2048
	ds_read_b128 v[166:169], v234 offset:3072
	ds_read_b128 v[170:173], v235
	ds_read_b128 v[174:177], v235 offset:1024
	ds_read_b128 v[178:181], v235 offset:2048
	ds_read_b128 v[182:185], v235 offset:3072
	s_add_u32 s6, s4, 0x100
	s_addc_u32 s7, s5, 0
	s_cmp_eq_u32 s80, 28
	s_cselect_b32 s57, s35, s7
	s_cselect_b32 s56, s43, s6
	s_cselect_b32 s19, s31, s79
	s_cselect_b32 s18, vcc_lo, vcc_hi
	v_lshl_add_u64 v[218:219], s[4:5], 0, v[154:155]
	s_add_i32 m0, s65, 0xc000
	ds_read_b128 v[186:189], v236
	ds_read_b128 v[190:193], v236 offset:1024
	ds_read_b128 v[194:197], v236 offset:2048
	ds_read_b128 v[198:201], v236 offset:3072
	ds_read_b128 v[202:205], v236 offset:4096
	ds_read_b128 v[206:209], v236 offset:5120
	ds_read_b128 v[210:213], v236 offset:6144
	ds_read_b128 v[214:217], v236 offset:7168
	global_load_lds_dwordx4 v[218:219], off
	v_lshl_add_u64 v[218:219], s[4:5], 0, v[156:157]
	s_add_i32 m0, s65, 0xe000
	s_nop 0
	global_load_lds_dwordx4 v[218:219], off
	s_waitcnt vmcnt(8)
	s_waitcnt lgkmcnt(0)
	s_barrier
	s_waitcnt lgkmcnt(0)
	v_mfma_i32_16x16x64_i8 v[118:121], v[130:133], v[186:189], 0
	v_mfma_i32_16x16x64_i8 v[102:105], v[162:165], v[186:189], 0
	v_mfma_i32_16x16x64_i8 v[114:117], v[130:133], v[194:197], 0
	v_mfma_i32_16x16x64_i8 v[98:101], v[162:165], v[194:197], 0
	v_mfma_i32_16x16x64_i8 v[126:129], v[130:133], v[202:205], 0
	v_mfma_i32_16x16x64_i8 v[110:113], v[162:165], v[202:205], 0
	v_mfma_i32_16x16x64_i8 v[122:125], v[130:133], v[210:213], 0
	v_mfma_i32_16x16x64_i8 v[106:109], v[162:165], v[210:213], 0
	v_mfma_i32_16x16x64_i8 v[118:121], v[134:137], v[190:193], v[118:121]
	v_mfma_i32_16x16x64_i8 v[102:105], v[166:169], v[190:193], v[102:105]
	v_mfma_i32_16x16x64_i8 v[114:117], v[134:137], v[198:201], v[114:117]
	v_mfma_i32_16x16x64_i8 v[98:101], v[166:169], v[198:201], v[98:101]
	v_mfma_i32_16x16x64_i8 v[126:129], v[134:137], v[206:209], v[126:129]
	v_mfma_i32_16x16x64_i8 v[110:113], v[166:169], v[206:209], v[110:113]
	v_mfma_i32_16x16x64_i8 v[122:125], v[134:137], v[214:217], v[122:125]
	v_mfma_i32_16x16x64_i8 v[106:109], v[166:169], v[214:217], v[106:109]
	v_mfma_i32_16x16x64_i8 v[86:89], v[170:173], v[186:189], 0
	v_mfma_i32_16x16x64_i8 v[70:73], v[178:181], v[186:189], 0
	v_mfma_i32_16x16x64_i8 v[82:85], v[170:173], v[194:197], 0
	v_mfma_i32_16x16x64_i8 v[66:69], v[178:181], v[194:197], 0
	v_mfma_i32_16x16x64_i8 v[94:97], v[170:173], v[202:205], 0
	v_mfma_i32_16x16x64_i8 v[78:81], v[178:181], v[202:205], 0
	v_mfma_i32_16x16x64_i8 v[90:93], v[170:173], v[210:213], 0
	v_mfma_i32_16x16x64_i8 v[74:77], v[178:181], v[210:213], 0
	v_mfma_i32_16x16x64_i8 v[86:89], v[174:177], v[190:193], v[86:89]
	v_mfma_i32_16x16x64_i8 v[70:73], v[182:185], v[190:193], v[70:73]
	v_mfma_i32_16x16x64_i8 v[82:85], v[174:177], v[198:201], v[82:85]
	v_mfma_i32_16x16x64_i8 v[66:69], v[182:185], v[198:201], v[66:69]
	v_mfma_i32_16x16x64_i8 v[94:97], v[174:177], v[206:209], v[94:97]
	v_mfma_i32_16x16x64_i8 v[78:81], v[182:185], v[206:209], v[78:81]
	v_mfma_i32_16x16x64_i8 v[90:93], v[174:177], v[214:217], v[90:93]
	v_mfma_i32_16x16x64_i8 v[74:77], v[182:185], v[214:217], v[74:77]
	s_barrier
	s_add_i32 s4, s97, s63
	v_lshl_add_u64 v[218:219], s[18:19], 0, v[144:145]
	s_mov_b32 m0, s4
	ds_read_b128 v[186:189], v236 offset:16384
	ds_read_b128 v[190:193], v236 offset:17408
	ds_read_b128 v[194:197], v236 offset:18432
	ds_read_b128 v[198:201], v236 offset:19456
	ds_read_b128 v[202:205], v236 offset:20480
	ds_read_b128 v[206:209], v236 offset:21504
	ds_read_b128 v[210:213], v236 offset:22528
	ds_read_b128 v[214:217], v236 offset:23552
	global_load_lds_dwordx4 v[218:219], off
	s_add_i32 m0, s4, 0x2000
	s_add_u32 s4, s18, 0x80000
	v_lshl_add_u64 v[220:221], s[18:19], 0, v[148:149]
	s_addc_u32 s5, s19, 0
	s_add_i32 s81, s0, s63
	global_load_lds_dwordx4 v[220:221], off
	v_lshl_add_u64 v[222:223], s[4:5], 0, v[144:145]
	s_mov_b32 m0, s81
	v_lshl_add_u64 v[224:225], s[56:57], 0, v[146:147]
	global_load_lds_dwordx4 v[222:223], off
	v_lshl_add_u64 v[222:223], s[4:5], 0, v[148:149]
	s_add_i32 m0, s81, 0x2000
	s_nop 0
	global_load_lds_dwordx4 v[222:223], off
	v_lshl_add_u64 v[222:223], s[56:57], 0, v[142:143]
	s_mov_b32 m0, s65
	s_nop 0
	global_load_lds_dwordx4 v[222:223], off
	s_mov_b32 m0, s66
	s_nop 0
	global_load_lds_dwordx4 v[224:225], off
	s_waitcnt vmcnt(8)
	s_waitcnt lgkmcnt(0)
	s_barrier
	s_waitcnt lgkmcnt(0)
	v_mfma_i32_16x16x64_i8 v[54:57], v[130:133], v[186:189], 0
	v_mfma_i32_16x16x64_i8 v[18:21], v[162:165], v[186:189], 0
	v_mfma_i32_16x16x64_i8 v[50:53], v[130:133], v[194:197], 0
	v_mfma_i32_16x16x64_i8 v[22:25], v[162:165], v[194:197], 0
	v_mfma_i32_16x16x64_i8 v[62:65], v[130:133], v[202:205], 0
	v_mfma_i32_16x16x64_i8 v[30:33], v[162:165], v[202:205], 0
	v_mfma_i32_16x16x64_i8 v[58:61], v[130:133], v[210:213], 0
	v_mfma_i32_16x16x64_i8 v[26:29], v[162:165], v[210:213], 0
	v_mfma_i32_16x16x64_i8 v[54:57], v[134:137], v[190:193], v[54:57]
	v_mfma_i32_16x16x64_i8 v[18:21], v[166:169], v[190:193], v[18:21]
	v_mfma_i32_16x16x64_i8 v[50:53], v[134:137], v[198:201], v[50:53]
	v_mfma_i32_16x16x64_i8 v[22:25], v[166:169], v[198:201], v[22:25]
	v_mfma_i32_16x16x64_i8 v[62:65], v[134:137], v[206:209], v[62:65]
	v_mfma_i32_16x16x64_i8 v[30:33], v[166:169], v[206:209], v[30:33]
	v_mfma_i32_16x16x64_i8 v[58:61], v[134:137], v[214:217], v[58:61]
	v_mfma_i32_16x16x64_i8 v[26:29], v[166:169], v[214:217], v[26:29]
	v_mfma_i32_16x16x64_i8 v[46:49], v[170:173], v[186:189], 0
	v_mfma_i32_16x16x64_i8 v[14:17], v[178:181], v[186:189], 0
	v_mfma_i32_16x16x64_i8 v[42:45], v[170:173], v[194:197], 0
	v_mfma_i32_16x16x64_i8 v[10:13], v[178:181], v[194:197], 0
	v_mfma_i32_16x16x64_i8 v[38:41], v[170:173], v[202:205], 0
	v_mfma_i32_16x16x64_i8 v[6:9], v[178:181], v[202:205], 0
	v_mfma_i32_16x16x64_i8 v[34:37], v[170:173], v[210:213], 0
	v_mfma_i32_16x16x64_i8 v[2:5], v[178:181], v[210:213], 0
	v_mfma_i32_16x16x64_i8 v[46:49], v[174:177], v[190:193], v[46:49]
	v_mfma_i32_16x16x64_i8 v[14:17], v[182:185], v[190:193], v[14:17]
	v_mfma_i32_16x16x64_i8 v[42:45], v[174:177], v[198:201], v[42:45]
	v_mfma_i32_16x16x64_i8 v[10:13], v[182:185], v[198:201], v[10:13]
	v_mfma_i32_16x16x64_i8 v[38:41], v[174:177], v[206:209], v[38:41]
	v_mfma_i32_16x16x64_i8 v[6:9], v[182:185], v[206:209], v[6:9]
	v_mfma_i32_16x16x64_i8 v[34:37], v[174:177], v[214:217], v[34:37]
	v_mfma_i32_16x16x64_i8 v[2:5], v[182:185], v[214:217], v[2:5]
	s_barrier
	s_add_i32 s81, 0, 0x18000
	s_add_i32 s82, 0, 0x1c000
	v_add_u32_e32 v166, s81, v232
	v_add_u32_e32 v182, s82, v232
	ds_read_b128 v[130:133], v166
	ds_read_b128 v[134:137], v166 offset:1024
	ds_read_b128 v[162:165], v166 offset:2048
	ds_read_b128 v[166:169], v166 offset:3072
	ds_read_b128 v[170:173], v182
	ds_read_b128 v[174:177], v182 offset:1024
	ds_read_b128 v[178:181], v182 offset:2048
	ds_read_b128 v[182:185], v182 offset:3072
	s_add_u32 s4, s56, 0x80000
	s_addc_u32 s5, s57, 0
	s_mov_b32 m0, s67
	v_lshl_add_u64 v[226:227], s[4:5], 0, v[142:143]
	ds_read_b128 v[186:189], v236 offset:32768
	ds_read_b128 v[190:193], v236 offset:33792
	ds_read_b128 v[194:197], v236 offset:34816
	ds_read_b128 v[198:201], v236 offset:35840
	ds_read_b128 v[202:205], v236 offset:36864
	ds_read_b128 v[206:209], v236 offset:37888
	ds_read_b128 v[210:213], v236 offset:38912
	ds_read_b128 v[214:217], v236 offset:39936
	global_load_lds_dwordx4 v[226:227], off
	v_lshl_add_u64 v[226:227], s[4:5], 0, v[146:147]
	s_mov_b32 m0, s68
	s_nop 0
	global_load_lds_dwordx4 v[226:227], off
	s_waitcnt vmcnt(8)
	s_waitcnt lgkmcnt(0)
	s_barrier
	s_waitcnt lgkmcnt(0)
	v_mfma_i32_16x16x64_i8 v[118:121], v[130:133], v[186:189], v[118:121]
	v_mfma_i32_16x16x64_i8 v[102:105], v[162:165], v[186:189], v[102:105]
	v_mfma_i32_16x16x64_i8 v[114:117], v[130:133], v[194:197], v[114:117]
	v_mfma_i32_16x16x64_i8 v[98:101], v[162:165], v[194:197], v[98:101]
	v_mfma_i32_16x16x64_i8 v[126:129], v[130:133], v[202:205], v[126:129]
	v_mfma_i32_16x16x64_i8 v[110:113], v[162:165], v[202:205], v[110:113]
	v_mfma_i32_16x16x64_i8 v[122:125], v[130:133], v[210:213], v[122:125]
	v_mfma_i32_16x16x64_i8 v[106:109], v[162:165], v[210:213], v[106:109]
	v_mfma_i32_16x16x64_i8 v[118:121], v[134:137], v[190:193], v[118:121]
	v_mfma_i32_16x16x64_i8 v[102:105], v[166:169], v[190:193], v[102:105]
	v_mfma_i32_16x16x64_i8 v[114:117], v[134:137], v[198:201], v[114:117]
	v_mfma_i32_16x16x64_i8 v[98:101], v[166:169], v[198:201], v[98:101]
	v_mfma_i32_16x16x64_i8 v[126:129], v[134:137], v[206:209], v[126:129]
	v_mfma_i32_16x16x64_i8 v[110:113], v[166:169], v[206:209], v[110:113]
	v_mfma_i32_16x16x64_i8 v[122:125], v[134:137], v[214:217], v[122:125]
	v_mfma_i32_16x16x64_i8 v[106:109], v[166:169], v[214:217], v[106:109]
	v_mfma_i32_16x16x64_i8 v[86:89], v[170:173], v[186:189], v[86:89]
	v_mfma_i32_16x16x64_i8 v[70:73], v[178:181], v[186:189], v[70:73]
	v_mfma_i32_16x16x64_i8 v[82:85], v[170:173], v[194:197], v[82:85]
	v_mfma_i32_16x16x64_i8 v[66:69], v[178:181], v[194:197], v[66:69]
	v_mfma_i32_16x16x64_i8 v[94:97], v[170:173], v[202:205], v[94:97]
	v_mfma_i32_16x16x64_i8 v[78:81], v[178:181], v[202:205], v[78:81]
	v_mfma_i32_16x16x64_i8 v[90:93], v[170:173], v[210:213], v[90:93]
	v_mfma_i32_16x16x64_i8 v[74:77], v[178:181], v[210:213], v[74:77]
	v_mfma_i32_16x16x64_i8 v[86:89], v[174:177], v[190:193], v[86:89]
	v_mfma_i32_16x16x64_i8 v[70:73], v[182:185], v[190:193], v[70:73]
	v_mfma_i32_16x16x64_i8 v[82:85], v[174:177], v[198:201], v[82:85]
	v_mfma_i32_16x16x64_i8 v[66:69], v[182:185], v[198:201], v[66:69]
	v_mfma_i32_16x16x64_i8 v[94:97], v[174:177], v[206:209], v[94:97]
	v_mfma_i32_16x16x64_i8 v[78:81], v[182:185], v[206:209], v[78:81]
	v_mfma_i32_16x16x64_i8 v[90:93], v[174:177], v[214:217], v[90:93]
	v_mfma_i32_16x16x64_i8 v[74:77], v[182:185], v[214:217], v[74:77]
	s_barrier
	s_add_i32 s4, s81, s63
	v_lshl_add_u64 v[218:219], v[218:219], 0, s[22:23]
	s_mov_b32 m0, s4
	ds_read_b128 v[186:189], v236 offset:49152
	ds_read_b128 v[190:193], v236 offset:50176
	ds_read_b128 v[194:197], v236 offset:51200
	ds_read_b128 v[198:201], v236 offset:52224
	ds_read_b128 v[202:205], v236 offset:53248
	ds_read_b128 v[206:209], v236 offset:54272
	ds_read_b128 v[210:213], v236 offset:55296
	ds_read_b128 v[214:217], v236 offset:56320
	global_load_lds_dwordx4 v[218:219], off
	s_add_i32 m0, s4, 0x2000
	s_add_u32 s4, s18, 0x80080
	v_lshl_add_u64 v[218:219], v[220:221], 0, s[22:23]
	s_addc_u32 s5, s19, 0
	s_add_i32 s18, s82, s63
	global_load_lds_dwordx4 v[218:219], off
	v_lshl_add_u64 v[218:219], s[4:5], 0, v[144:145]
	s_mov_b32 m0, s18
	s_nop 0
	global_load_lds_dwordx4 v[218:219], off
	v_lshl_add_u64 v[218:219], s[4:5], 0, v[148:149]
	s_add_i32 m0, s18, 0x2000
	s_nop 0
	global_load_lds_dwordx4 v[218:219], off
	v_lshl_add_u64 v[218:219], v[222:223], 0, s[22:23]
	s_mov_b32 m0, s77
	s_nop 0
	global_load_lds_dwordx4 v[218:219], off
	v_lshl_add_u64 v[218:219], v[224:225], 0, s[22:23]
	s_mov_b32 m0, s78
	s_nop 0
	global_load_lds_dwordx4 v[218:219], off
	s_waitcnt vmcnt(8)
	s_waitcnt lgkmcnt(0)
	s_barrier
	s_waitcnt lgkmcnt(0)
	v_mfma_i32_16x16x64_i8 v[54:57], v[130:133], v[186:189], v[54:57]
	v_mfma_i32_16x16x64_i8 v[18:21], v[162:165], v[186:189], v[18:21]
	v_mfma_i32_16x16x64_i8 v[50:53], v[130:133], v[194:197], v[50:53]
	v_mfma_i32_16x16x64_i8 v[22:25], v[162:165], v[194:197], v[22:25]
	v_mfma_i32_16x16x64_i8 v[62:65], v[130:133], v[202:205], v[62:65]
	v_mfma_i32_16x16x64_i8 v[30:33], v[162:165], v[202:205], v[30:33]
	v_mfma_i32_16x16x64_i8 v[58:61], v[130:133], v[210:213], v[58:61]
	v_mfma_i32_16x16x64_i8 v[26:29], v[162:165], v[210:213], v[26:29]
	v_mfma_i32_16x16x64_i8 v[54:57], v[134:137], v[190:193], v[54:57]
	v_mfma_i32_16x16x64_i8 v[18:21], v[166:169], v[190:193], v[18:21]
	v_mfma_i32_16x16x64_i8 v[50:53], v[134:137], v[198:201], v[50:53]
	v_mfma_i32_16x16x64_i8 v[22:25], v[166:169], v[198:201], v[22:25]
	v_mfma_i32_16x16x64_i8 v[62:65], v[134:137], v[206:209], v[62:65]
	v_mfma_i32_16x16x64_i8 v[30:33], v[166:169], v[206:209], v[30:33]
	v_mfma_i32_16x16x64_i8 v[58:61], v[134:137], v[214:217], v[58:61]
	v_mfma_i32_16x16x64_i8 v[26:29], v[166:169], v[214:217], v[26:29]
	v_mfma_i32_16x16x64_i8 v[46:49], v[170:173], v[186:189], v[46:49]
	v_mfma_i32_16x16x64_i8 v[14:17], v[178:181], v[186:189], v[14:17]
	v_mfma_i32_16x16x64_i8 v[42:45], v[170:173], v[194:197], v[42:45]
	v_mfma_i32_16x16x64_i8 v[10:13], v[178:181], v[194:197], v[10:13]
	v_mfma_i32_16x16x64_i8 v[38:41], v[170:173], v[202:205], v[38:41]
	v_mfma_i32_16x16x64_i8 v[6:9], v[178:181], v[202:205], v[6:9]
	v_mfma_i32_16x16x64_i8 v[34:37], v[170:173], v[210:213], v[34:37]
	v_mfma_i32_16x16x64_i8 v[2:5], v[178:181], v[210:213], v[2:5]
	v_mfma_i32_16x16x64_i8 v[46:49], v[174:177], v[190:193], v[46:49]
	v_mfma_i32_16x16x64_i8 v[14:17], v[182:185], v[190:193], v[14:17]
	v_mfma_i32_16x16x64_i8 v[42:45], v[174:177], v[198:201], v[42:45]
	v_mfma_i32_16x16x64_i8 v[10:13], v[182:185], v[198:201], v[10:13]
	v_mfma_i32_16x16x64_i8 v[38:41], v[174:177], v[206:209], v[38:41]
	v_mfma_i32_16x16x64_i8 v[6:9], v[182:185], v[206:209], v[6:9]
	v_mfma_i32_16x16x64_i8 v[34:37], v[174:177], v[214:217], v[34:37]
	v_mfma_i32_16x16x64_i8 v[2:5], v[182:185], v[214:217], v[2:5]
	s_barrier
	s_add_i32 s80, s80, 2
	s_add_u32 vcc_hi, vcc_hi, 0x100
	s_addc_u32 s79, s79, 0
	s_cmp_gt_u32 s80, 29
	s_mov_b64 s[4:5], s[6:7]

.LBB0_1553:
	s_add_u32 s64, s26, 0x100
	s_addc_u32 s65, s27, 0
	s_mov_b32 s66, -2
	s_waitcnt lgkmcnt(0)
	ds_read_b128 v[114:117], v247
	ds_read_b128 v[118:121], v247 offset:1024
	ds_read_b128 v[126:129], v247 offset:2048
	ds_read_b128 v[134:137], v247 offset:3072
	ds_read_b128 v[138:141], v248
	ds_read_b128 v[142:145], v248 offset:1024
	ds_read_b128 v[154:157], v248 offset:2048
	ds_read_b128 v[158:161], v248 offset:3072
	s_add_u32 s4, s18, 0x100
	s_addc_u32 s5, s19, 0
	s_cmpk_eq_i32 s66, 0xdc
	s_cselect_b32 s29, s23, s5
	s_cselect_b32 s28, s22, s4
	s_cselect_b32 s27, s25, s65
	s_cselect_b32 s26, s24, s64
	v_lshl_add_u64 v[210:211], s[18:19], 0, v[202:203]
	s_add_i32 m0, s17, 0xc000
	ds_read_b128 v[162:165], v249
	ds_read_b128 v[166:169], v249 offset:1024
	ds_read_b128 v[170:173], v249 offset:2048
	ds_read_b128 v[174:177], v249 offset:3072
	ds_read_b128 v[178:181], v249 offset:4096
	ds_read_b128 v[182:185], v249 offset:5120
	ds_read_b128 v[186:189], v249 offset:6144
	ds_read_b128 v[190:193], v249 offset:7168
	global_load_lds_dwordx4 v[210:211], off
	v_lshl_add_u64 v[210:211], s[18:19], 0, v[204:205]
	s_add_i32 m0, s17, 0xe000
	s_nop 0
	global_load_lds_dwordx4 v[210:211], off
	s_waitcnt vmcnt(8)
	s_waitcnt lgkmcnt(0)
	s_barrier
	s_waitcnt lgkmcnt(0)
	v_mfma_f32_16x16x32_bf16 v[150:153], v[114:117], v[162:165], 0
	v_mfma_f32_16x16x32_bf16 v[146:149], v[126:129], v[162:165], 0
	v_mfma_f32_16x16x32_bf16 v[110:113], v[114:117], v[170:173], 0
	v_mfma_f32_16x16x32_bf16 v[106:109], v[126:129], v[170:173], 0
	v_mfma_f32_16x16x32_bf16 v[94:97], v[114:117], v[178:181], 0
	v_mfma_f32_16x16x32_bf16 v[90:93], v[126:129], v[178:181], 0
	v_mfma_f32_16x16x32_bf16 v[78:81], v[114:117], v[186:189], 0
	v_mfma_f32_16x16x32_bf16 v[74:77], v[126:129], v[186:189], 0
	v_mfma_f32_16x16x32_bf16 v[150:153], v[118:121], v[166:169], v[150:153]
	v_mfma_f32_16x16x32_bf16 v[146:149], v[134:137], v[166:169], v[146:149]
	v_mfma_f32_16x16x32_bf16 v[110:113], v[118:121], v[174:177], v[110:113]
	v_mfma_f32_16x16x32_bf16 v[106:109], v[134:137], v[174:177], v[106:109]
	v_mfma_f32_16x16x32_bf16 v[94:97], v[118:121], v[182:185], v[94:97]
	v_mfma_f32_16x16x32_bf16 v[90:93], v[134:137], v[182:185], v[90:93]
	v_mfma_f32_16x16x32_bf16 v[78:81], v[118:121], v[190:193], v[78:81]
	v_mfma_f32_16x16x32_bf16 v[74:77], v[134:137], v[190:193], v[74:77]
	v_mfma_f32_16x16x32_bf16 v[130:133], v[138:141], v[162:165], 0
	v_mfma_f32_16x16x32_bf16 v[122:125], v[154:157], v[162:165], 0
	v_mfma_f32_16x16x32_bf16 v[102:105], v[138:141], v[170:173], 0
	v_mfma_f32_16x16x32_bf16 v[98:101], v[154:157], v[170:173], 0
	v_mfma_f32_16x16x32_bf16 v[86:89], v[138:141], v[178:181], 0
	v_mfma_f32_16x16x32_bf16 v[82:85], v[154:157], v[178:181], 0
	v_mfma_f32_16x16x32_bf16 v[70:73], v[138:141], v[186:189], 0
	v_mfma_f32_16x16x32_bf16 v[66:69], v[154:157], v[186:189], 0
	v_mfma_f32_16x16x32_bf16 v[130:133], v[142:145], v[166:169], v[130:133]
	v_mfma_f32_16x16x32_bf16 v[122:125], v[158:161], v[166:169], v[122:125]
	v_mfma_f32_16x16x32_bf16 v[102:105], v[142:145], v[174:177], v[102:105]
	v_mfma_f32_16x16x32_bf16 v[98:101], v[158:161], v[174:177], v[98:101]
	v_mfma_f32_16x16x32_bf16 v[86:89], v[142:145], v[182:185], v[86:89]
	v_mfma_f32_16x16x32_bf16 v[82:85], v[158:161], v[182:185], v[82:85]
	v_mfma_f32_16x16x32_bf16 v[70:73], v[142:145], v[190:193], v[70:73]
	v_mfma_f32_16x16x32_bf16 v[66:69], v[158:161], v[190:193], v[66:69]
	s_barrier
	s_add_i32 s18, s42, s16
	v_lshl_add_u64 v[210:211], s[26:27], 0, v[196:197]
	s_mov_b32 m0, s18
	ds_read_b128 v[162:165], v249 offset:16384
	ds_read_b128 v[166:169], v249 offset:17408
	ds_read_b128 v[170:173], v249 offset:18432
	ds_read_b128 v[174:177], v249 offset:19456
	ds_read_b128 v[178:181], v249 offset:20480
	ds_read_b128 v[182:185], v249 offset:21504
	ds_read_b128 v[186:189], v249 offset:22528
	ds_read_b128 v[190:193], v249 offset:23552
	global_load_lds_dwordx4 v[210:211], off
	s_add_i32 m0, s18, 0x2000
	s_add_u32 s18, s26, 0x380000
	v_lshl_add_u64 v[212:213], s[26:27], 0, v[200:201]
	s_addc_u32 s19, s27, 0
	s_add_i32 s67, s43, s16
	global_load_lds_dwordx4 v[212:213], off
	v_lshl_add_u64 v[214:215], s[18:19], 0, v[196:197]
	s_mov_b32 m0, s67
	v_lshl_add_u64 v[216:217], s[28:29], 0, v[198:199]
	global_load_lds_dwordx4 v[214:215], off
	v_lshl_add_u64 v[214:215], s[18:19], 0, v[200:201]
	s_add_i32 m0, s67, 0x2000
	s_nop 0
	global_load_lds_dwordx4 v[214:215], off
	v_lshl_add_u64 v[214:215], s[28:29], 0, v[194:195]
	s_mov_b32 m0, s17
	s_nop 0
	global_load_lds_dwordx4 v[214:215], off
	s_mov_b32 m0, s30
	s_nop 0
	global_load_lds_dwordx4 v[216:217], off
	s_waitcnt vmcnt(8)
	s_waitcnt lgkmcnt(0)
	s_barrier
	s_waitcnt lgkmcnt(0)
	v_mfma_f32_16x16x32_bf16 v[62:65], v[114:117], v[162:165], 0
	v_mfma_f32_16x16x32_bf16 v[58:61], v[126:129], v[162:165], 0
	v_mfma_f32_16x16x32_bf16 v[46:49], v[114:117], v[170:173], 0
	v_mfma_f32_16x16x32_bf16 v[42:45], v[126:129], v[170:173], 0
	v_mfma_f32_16x16x32_bf16 v[30:33], v[114:117], v[178:181], 0
	v_mfma_f32_16x16x32_bf16 v[26:29], v[126:129], v[178:181], 0
	v_mfma_f32_16x16x32_bf16 v[14:17], v[114:117], v[186:189], 0
	v_mfma_f32_16x16x32_bf16 v[10:13], v[126:129], v[186:189], 0
	v_mfma_f32_16x16x32_bf16 v[62:65], v[118:121], v[166:169], v[62:65]
	v_mfma_f32_16x16x32_bf16 v[58:61], v[134:137], v[166:169], v[58:61]
	v_mfma_f32_16x16x32_bf16 v[46:49], v[118:121], v[174:177], v[46:49]
	v_mfma_f32_16x16x32_bf16 v[42:45], v[134:137], v[174:177], v[42:45]
	v_mfma_f32_16x16x32_bf16 v[30:33], v[118:121], v[182:185], v[30:33]
	v_mfma_f32_16x16x32_bf16 v[26:29], v[134:137], v[182:185], v[26:29]
	v_mfma_f32_16x16x32_bf16 v[14:17], v[118:121], v[190:193], v[14:17]
	v_mfma_f32_16x16x32_bf16 v[10:13], v[134:137], v[190:193], v[10:13]
	v_mfma_f32_16x16x32_bf16 v[54:57], v[138:141], v[162:165], 0
	v_mfma_f32_16x16x32_bf16 v[50:53], v[154:157], v[162:165], 0
	v_mfma_f32_16x16x32_bf16 v[38:41], v[138:141], v[170:173], 0
	v_mfma_f32_16x16x32_bf16 v[34:37], v[154:157], v[170:173], 0
	v_mfma_f32_16x16x32_bf16 v[22:25], v[138:141], v[178:181], 0
	v_mfma_f32_16x16x32_bf16 v[18:21], v[154:157], v[178:181], 0
	v_mfma_f32_16x16x32_bf16 v[6:9], v[138:141], v[186:189], 0
	v_mfma_f32_16x16x32_bf16 v[2:5], v[154:157], v[186:189], 0
	v_mfma_f32_16x16x32_bf16 v[54:57], v[142:145], v[166:169], v[54:57]
	v_mfma_f32_16x16x32_bf16 v[50:53], v[158:161], v[166:169], v[50:53]
	v_mfma_f32_16x16x32_bf16 v[38:41], v[142:145], v[174:177], v[38:41]
	v_mfma_f32_16x16x32_bf16 v[34:37], v[158:161], v[174:177], v[34:37]
	v_mfma_f32_16x16x32_bf16 v[22:25], v[142:145], v[182:185], v[22:25]
	v_mfma_f32_16x16x32_bf16 v[18:21], v[158:161], v[182:185], v[18:21]
	v_mfma_f32_16x16x32_bf16 v[6:9], v[142:145], v[190:193], v[6:9]
	v_mfma_f32_16x16x32_bf16 v[2:5], v[158:161], v[190:193], v[2:5]
	s_barrier
	s_add_i32 s67, 0, 0x18000
	s_add_i32 s68, 0, 0x1c000
	v_add_u32_e32 v134, s67, v244
	v_add_u32_e32 v158, s68, v244
	ds_read_b128 v[114:117], v134
	ds_read_b128 v[118:121], v134 offset:1024
	ds_read_b128 v[126:129], v134 offset:2048
	ds_read_b128 v[134:137], v134 offset:3072
	ds_read_b128 v[138:141], v158
	ds_read_b128 v[142:145], v158 offset:1024
	ds_read_b128 v[154:157], v158 offset:2048
	ds_read_b128 v[158:161], v158 offset:3072
	s_add_u32 s18, s28, 0x380000
	s_addc_u32 s19, s29, 0
	s_mov_b32 m0, s31
	v_lshl_add_u64 v[218:219], s[18:19], 0, v[194:195]
	ds_read_b128 v[162:165], v249 offset:32768
	ds_read_b128 v[166:169], v249 offset:33792
	ds_read_b128 v[170:173], v249 offset:34816
	ds_read_b128 v[174:177], v249 offset:35840
	ds_read_b128 v[178:181], v249 offset:36864
	ds_read_b128 v[182:185], v249 offset:37888
	ds_read_b128 v[186:189], v249 offset:38912
	ds_read_b128 v[190:193], v249 offset:39936
	global_load_lds_dwordx4 v[218:219], off
	v_lshl_add_u64 v[218:219], s[18:19], 0, v[198:199]
	s_mov_b32 m0, s34
	s_nop 0
	global_load_lds_dwordx4 v[218:219], off
	s_waitcnt vmcnt(8)
	s_waitcnt lgkmcnt(0)
	s_barrier
	s_waitcnt lgkmcnt(0)
	v_mfma_f32_16x16x32_bf16 v[150:153], v[114:117], v[162:165], v[150:153]
	v_mfma_f32_16x16x32_bf16 v[146:149], v[126:129], v[162:165], v[146:149]
	v_mfma_f32_16x16x32_bf16 v[110:113], v[114:117], v[170:173], v[110:113]
	v_mfma_f32_16x16x32_bf16 v[106:109], v[126:129], v[170:173], v[106:109]
	v_mfma_f32_16x16x32_bf16 v[94:97], v[114:117], v[178:181], v[94:97]
	v_mfma_f32_16x16x32_bf16 v[90:93], v[126:129], v[178:181], v[90:93]
	v_mfma_f32_16x16x32_bf16 v[78:81], v[114:117], v[186:189], v[78:81]
	v_mfma_f32_16x16x32_bf16 v[74:77], v[126:129], v[186:189], v[74:77]
	v_mfma_f32_16x16x32_bf16 v[150:153], v[118:121], v[166:169], v[150:153]
	v_mfma_f32_16x16x32_bf16 v[146:149], v[134:137], v[166:169], v[146:149]
	v_mfma_f32_16x16x32_bf16 v[110:113], v[118:121], v[174:177], v[110:113]
	v_mfma_f32_16x16x32_bf16 v[106:109], v[134:137], v[174:177], v[106:109]
	v_mfma_f32_16x16x32_bf16 v[94:97], v[118:121], v[182:185], v[94:97]
	v_mfma_f32_16x16x32_bf16 v[90:93], v[134:137], v[182:185], v[90:93]
	v_mfma_f32_16x16x32_bf16 v[78:81], v[118:121], v[190:193], v[78:81]
	v_mfma_f32_16x16x32_bf16 v[74:77], v[134:137], v[190:193], v[74:77]
	v_mfma_f32_16x16x32_bf16 v[130:133], v[138:141], v[162:165], v[130:133]
	v_mfma_f32_16x16x32_bf16 v[122:125], v[154:157], v[162:165], v[122:125]
	v_mfma_f32_16x16x32_bf16 v[102:105], v[138:141], v[170:173], v[102:105]
	v_mfma_f32_16x16x32_bf16 v[98:101], v[154:157], v[170:173], v[98:101]
	v_mfma_f32_16x16x32_bf16 v[86:89], v[138:141], v[178:181], v[86:89]
	v_mfma_f32_16x16x32_bf16 v[82:85], v[154:157], v[178:181], v[82:85]
	v_mfma_f32_16x16x32_bf16 v[70:73], v[138:141], v[186:189], v[70:73]
	v_mfma_f32_16x16x32_bf16 v[66:69], v[154:157], v[186:189], v[66:69]
	v_mfma_f32_16x16x32_bf16 v[130:133], v[142:145], v[166:169], v[130:133]
	v_mfma_f32_16x16x32_bf16 v[122:125], v[158:161], v[166:169], v[122:125]
	v_mfma_f32_16x16x32_bf16 v[102:105], v[142:145], v[174:177], v[102:105]
	v_mfma_f32_16x16x32_bf16 v[98:101], v[158:161], v[174:177], v[98:101]
	v_mfma_f32_16x16x32_bf16 v[86:89], v[142:145], v[182:185], v[86:89]
	v_mfma_f32_16x16x32_bf16 v[82:85], v[158:161], v[182:185], v[82:85]
	v_mfma_f32_16x16x32_bf16 v[70:73], v[142:145], v[190:193], v[70:73]
	v_mfma_f32_16x16x32_bf16 v[66:69], v[158:161], v[190:193], v[66:69]
	s_barrier
	s_add_i32 s18, s67, s16
	v_lshl_add_u64 v[210:211], v[210:211], 0, s[12:13]
	s_mov_b32 m0, s18
	ds_read_b128 v[162:165], v249 offset:49152
	ds_read_b128 v[166:169], v249 offset:50176
	ds_read_b128 v[170:173], v249 offset:51200
	ds_read_b128 v[174:177], v249 offset:52224
	ds_read_b128 v[178:181], v249 offset:53248
	ds_read_b128 v[182:185], v249 offset:54272
	ds_read_b128 v[186:189], v249 offset:55296
	ds_read_b128 v[190:193], v249 offset:56320
	global_load_lds_dwordx4 v[210:211], off
	s_add_i32 m0, s18, 0x2000
	s_add_u32 s18, s26, 0x380080
	v_lshl_add_u64 v[210:211], v[212:213], 0, s[12:13]
	s_addc_u32 s19, s27, 0
	s_add_i32 s26, s68, s16
	global_load_lds_dwordx4 v[210:211], off
	v_lshl_add_u64 v[210:211], s[18:19], 0, v[196:197]
	s_mov_b32 m0, s26
	s_nop 0
	global_load_lds_dwordx4 v[210:211], off
	v_lshl_add_u64 v[210:211], s[18:19], 0, v[200:201]
	s_add_i32 m0, s26, 0x2000
	s_nop 0
	global_load_lds_dwordx4 v[210:211], off
	v_lshl_add_u64 v[210:211], v[214:215], 0, s[12:13]
	s_mov_b32 m0, s38
	s_nop 0
	global_load_lds_dwordx4 v[210:211], off
	v_lshl_add_u64 v[210:211], v[216:217], 0, s[12:13]
	s_mov_b32 m0, s39
	s_nop 0
	global_load_lds_dwordx4 v[210:211], off
	s_waitcnt vmcnt(8)
	s_waitcnt lgkmcnt(0)
	s_barrier
	s_waitcnt lgkmcnt(0)
	v_mfma_f32_16x16x32_bf16 v[62:65], v[114:117], v[162:165], v[62:65]
	v_mfma_f32_16x16x32_bf16 v[58:61], v[126:129], v[162:165], v[58:61]
	v_mfma_f32_16x16x32_bf16 v[46:49], v[114:117], v[170:173], v[46:49]
	v_mfma_f32_16x16x32_bf16 v[42:45], v[126:129], v[170:173], v[42:45]
	v_mfma_f32_16x16x32_bf16 v[30:33], v[114:117], v[178:181], v[30:33]
	v_mfma_f32_16x16x32_bf16 v[26:29], v[126:129], v[178:181], v[26:29]
	v_mfma_f32_16x16x32_bf16 v[14:17], v[114:117], v[186:189], v[14:17]
	v_mfma_f32_16x16x32_bf16 v[10:13], v[126:129], v[186:189], v[10:13]
	v_mfma_f32_16x16x32_bf16 v[62:65], v[118:121], v[166:169], v[62:65]
	v_mfma_f32_16x16x32_bf16 v[58:61], v[134:137], v[166:169], v[58:61]
	v_mfma_f32_16x16x32_bf16 v[46:49], v[118:121], v[174:177], v[46:49]
	v_mfma_f32_16x16x32_bf16 v[42:45], v[134:137], v[174:177], v[42:45]
	v_mfma_f32_16x16x32_bf16 v[30:33], v[118:121], v[182:185], v[30:33]
	v_mfma_f32_16x16x32_bf16 v[26:29], v[134:137], v[182:185], v[26:29]
	v_mfma_f32_16x16x32_bf16 v[14:17], v[118:121], v[190:193], v[14:17]
	v_mfma_f32_16x16x32_bf16 v[10:13], v[134:137], v[190:193], v[10:13]
	v_mfma_f32_16x16x32_bf16 v[54:57], v[138:141], v[162:165], v[54:57]
	v_mfma_f32_16x16x32_bf16 v[50:53], v[154:157], v[162:165], v[50:53]
	v_mfma_f32_16x16x32_bf16 v[38:41], v[138:141], v[170:173], v[38:41]
	v_mfma_f32_16x16x32_bf16 v[34:37], v[154:157], v[170:173], v[34:37]
	v_mfma_f32_16x16x32_bf16 v[22:25], v[138:141], v[178:181], v[22:25]
	v_mfma_f32_16x16x32_bf16 v[18:21], v[154:157], v[178:181], v[18:21]
	v_mfma_f32_16x16x32_bf16 v[6:9], v[138:141], v[186:189], v[6:9]
	v_mfma_f32_16x16x32_bf16 v[2:5], v[154:157], v[186:189], v[2:5]
	v_mfma_f32_16x16x32_bf16 v[54:57], v[142:145], v[166:169], v[54:57]
	v_mfma_f32_16x16x32_bf16 v[50:53], v[158:161], v[166:169], v[50:53]
	v_mfma_f32_16x16x32_bf16 v[38:41], v[142:145], v[174:177], v[38:41]
	v_mfma_f32_16x16x32_bf16 v[34:37], v[158:161], v[174:177], v[34:37]
	v_mfma_f32_16x16x32_bf16 v[22:25], v[142:145], v[182:185], v[22:25]
	v_mfma_f32_16x16x32_bf16 v[18:21], v[158:161], v[182:185], v[18:21]
	v_mfma_f32_16x16x32_bf16 v[6:9], v[142:145], v[190:193], v[6:9]
	v_mfma_f32_16x16x32_bf16 v[2:5], v[158:161], v[190:193], v[2:5]
	s_barrier
	s_add_i32 s66, s66, 2
	s_add_u32 s64, s64, 0x100
	s_addc_u32 s65, s65, 0
	s_cmpk_gt_u32 s66, 0xdd
	s_mov_b64 s[18:19], s[4:5]

.LBB0_1646:
	s_ashr_i32 s63, s62, 31
	s_lshl_b64 s[0:1], s[62:63], 21
	s_add_u32 s64, s52, s0
	s_addc_u32 s65, s53, s1
	s_and_b64 s[0:1], s[4:5], exec
	s_cselect_b32 s0, s65, s11
	s_cselect_b32 s1, s64, s10
	s_ashr_i32 s61, s60, 31
	s_lshl_b64 s[16:17], s[60:61], 21
	s_add_u32 s66, s31, s16
	s_addc_u32 s67, s35, s17
	s_and_b64 s[16:17], s[4:5], exec
	s_cselect_b32 s7, s67, s19
	s_cselect_b32 s9, s66, s18
	s_add_u32 s10, s10, 0x100080
	s_addc_u32 s11, s11, 0
	s_add_u32 s16, s18, 0x100
	s_addc_u32 s17, s19, 0
	s_mov_b32 s61, -2
	s_waitcnt lgkmcnt(0)
	ds_read_b128 v[30:33], v200
	ds_read_b128 v[38:41], v200 offset:1024
	ds_read_b128 v[42:45], v200 offset:2048
	ds_read_b128 v[50:53], v200 offset:3072
	ds_read_b128 v[164:167], v201
	ds_read_b128 v[168:171], v201 offset:1024
	ds_read_b128 v[172:175], v201 offset:2048
	ds_read_b128 v[176:179], v201 offset:3072
	s_add_u32 s18, s10, 0xfff00080
	s_addc_u32 s19, s11, -1
	s_cmp_eq_u32 s61, 60
	s_cselect_b32 s69, s0, s19
	s_cselect_b32 s68, s1, s18
	s_cselect_b32 s19, s7, s17
	s_cselect_b32 s18, s9, s16
	v_lshl_add_u64 v[222:223], s[10:11], 0, v[156:157]
	s_add_i32 m0, s39, 0xc000
	ds_read_b128 v[180:183], v202
	ds_read_b128 v[184:187], v202 offset:1024
	ds_read_b128 v[188:191], v202 offset:2048
	ds_read_b128 v[192:195], v202 offset:3072
	ds_read_b128 v[206:209], v202 offset:4096
	ds_read_b128 v[210:213], v202 offset:5120
	ds_read_b128 v[214:217], v202 offset:6144
	ds_read_b128 v[218:221], v202 offset:7168
	global_load_lds_dwordx4 v[222:223], off
	v_lshl_add_u64 v[222:223], s[10:11], 0, v[158:159]
	s_add_i32 m0, s39, 0xe000
	s_nop 0
	global_load_lds_dwordx4 v[222:223], off
	s_waitcnt vmcnt(8)
	s_waitcnt lgkmcnt(0)
	s_barrier
	s_waitcnt lgkmcnt(0)
	v_mfma_f32_16x16x32_bf16 v[138:141], v[30:33], v[180:183], 0
	v_mfma_f32_16x16x32_bf16 v[142:145], v[42:45], v[180:183], 0
	v_mfma_f32_16x16x32_bf16 v[122:125], v[30:33], v[188:191], 0
	v_mfma_f32_16x16x32_bf16 v[126:129], v[42:45], v[188:191], 0
	v_mfma_f32_16x16x32_bf16 v[106:109], v[30:33], v[206:209], 0
	v_mfma_f32_16x16x32_bf16 v[110:113], v[42:45], v[206:209], 0
	v_mfma_f32_16x16x32_bf16 v[90:93], v[30:33], v[214:217], 0
	v_mfma_f32_16x16x32_bf16 v[94:97], v[42:45], v[214:217], 0
	v_mfma_f32_16x16x32_bf16 v[138:141], v[38:41], v[184:187], v[138:141]
	v_mfma_f32_16x16x32_bf16 v[142:145], v[50:53], v[184:187], v[142:145]
	v_mfma_f32_16x16x32_bf16 v[122:125], v[38:41], v[192:195], v[122:125]
	v_mfma_f32_16x16x32_bf16 v[126:129], v[50:53], v[192:195], v[126:129]
	v_mfma_f32_16x16x32_bf16 v[106:109], v[38:41], v[210:213], v[106:109]
	v_mfma_f32_16x16x32_bf16 v[110:113], v[50:53], v[210:213], v[110:113]
	v_mfma_f32_16x16x32_bf16 v[90:93], v[38:41], v[218:221], v[90:93]
	v_mfma_f32_16x16x32_bf16 v[94:97], v[50:53], v[218:221], v[94:97]
	v_mfma_f32_16x16x32_bf16 v[130:133], v[164:167], v[180:183], 0
	v_mfma_f32_16x16x32_bf16 v[134:137], v[172:175], v[180:183], 0
	v_mfma_f32_16x16x32_bf16 v[114:117], v[164:167], v[188:191], 0
	v_mfma_f32_16x16x32_bf16 v[118:121], v[172:175], v[188:191], 0
	v_mfma_f32_16x16x32_bf16 v[98:101], v[164:167], v[206:209], 0
	v_mfma_f32_16x16x32_bf16 v[102:105], v[172:175], v[206:209], 0
	v_mfma_f32_16x16x32_bf16 v[82:85], v[164:167], v[214:217], 0
	v_mfma_f32_16x16x32_bf16 v[86:89], v[172:175], v[214:217], 0
	v_mfma_f32_16x16x32_bf16 v[130:133], v[168:171], v[184:187], v[130:133]
	v_mfma_f32_16x16x32_bf16 v[134:137], v[176:179], v[184:187], v[134:137]
	v_mfma_f32_16x16x32_bf16 v[114:117], v[168:171], v[192:195], v[114:117]
	v_mfma_f32_16x16x32_bf16 v[118:121], v[176:179], v[192:195], v[118:121]
	v_mfma_f32_16x16x32_bf16 v[98:101], v[168:171], v[210:213], v[98:101]
	v_mfma_f32_16x16x32_bf16 v[102:105], v[176:179], v[210:213], v[102:105]
	v_mfma_f32_16x16x32_bf16 v[82:85], v[168:171], v[218:221], v[82:85]
	v_mfma_f32_16x16x32_bf16 v[86:89], v[176:179], v[218:221], v[86:89]
	s_barrier
	s_add_i32 s63, s77, s37
	v_lshl_add_u64 v[222:223], s[18:19], 0, v[148:149]
	s_mov_b32 m0, s63
	ds_read_b128 v[180:183], v202 offset:16384
	ds_read_b128 v[184:187], v202 offset:17408
	ds_read_b128 v[188:191], v202 offset:18432
	ds_read_b128 v[192:195], v202 offset:19456
	ds_read_b128 v[206:209], v202 offset:20480
	ds_read_b128 v[210:213], v202 offset:21504
	ds_read_b128 v[214:217], v202 offset:22528
	ds_read_b128 v[218:221], v202 offset:23552
	global_load_lds_dwordx4 v[222:223], off
	s_add_i32 m0, s63, 0x2000
	s_add_u32 s82, s18, 0x100000
	v_lshl_add_u64 v[224:225], s[18:19], 0, v[152:153]
	s_addc_u32 s83, s19, 0
	s_add_i32 s63, s78, s37
	global_load_lds_dwordx4 v[224:225], off
	v_lshl_add_u64 v[226:227], s[82:83], 0, v[148:149]
	s_mov_b32 m0, s63
	v_lshl_add_u64 v[228:229], s[68:69], 0, v[150:151]
	global_load_lds_dwordx4 v[226:227], off
	v_lshl_add_u64 v[226:227], s[82:83], 0, v[152:153]
	s_add_i32 m0, s63, 0x2000
	s_nop 0
	global_load_lds_dwordx4 v[226:227], off
	v_lshl_add_u64 v[226:227], s[68:69], 0, v[146:147]
	s_mov_b32 m0, s39
	s_nop 0
	global_load_lds_dwordx4 v[226:227], off
	s_mov_b32 m0, s41
	s_nop 0
	global_load_lds_dwordx4 v[228:229], off
	s_waitcnt vmcnt(8)
	s_waitcnt lgkmcnt(0)
	s_barrier
	s_waitcnt lgkmcnt(0)
	v_mfma_f32_16x16x32_bf16 v[74:77], v[30:33], v[180:183], 0
	v_mfma_f32_16x16x32_bf16 v[78:81], v[42:45], v[180:183], 0
	v_mfma_f32_16x16x32_bf16 v[58:61], v[30:33], v[188:191], 0
	v_mfma_f32_16x16x32_bf16 v[62:65], v[42:45], v[188:191], 0
	v_mfma_f32_16x16x32_bf16 v[26:29], v[30:33], v[206:209], 0
	v_mfma_f32_16x16x32_bf16 v[34:37], v[42:45], v[206:209], 0
	v_mfma_f32_16x16x32_bf16 v[10:13], v[30:33], v[214:217], 0
	v_mfma_f32_16x16x32_bf16 v[14:17], v[42:45], v[214:217], 0
	v_mfma_f32_16x16x32_bf16 v[74:77], v[38:41], v[184:187], v[74:77]
	v_mfma_f32_16x16x32_bf16 v[78:81], v[50:53], v[184:187], v[78:81]
	v_mfma_f32_16x16x32_bf16 v[58:61], v[38:41], v[192:195], v[58:61]
	v_mfma_f32_16x16x32_bf16 v[62:65], v[50:53], v[192:195], v[62:65]
	v_mfma_f32_16x16x32_bf16 v[26:29], v[38:41], v[210:213], v[26:29]
	v_mfma_f32_16x16x32_bf16 v[34:37], v[50:53], v[210:213], v[34:37]
	v_mfma_f32_16x16x32_bf16 v[10:13], v[38:41], v[218:221], v[10:13]
	v_mfma_f32_16x16x32_bf16 v[14:17], v[50:53], v[218:221], v[14:17]
	v_mfma_f32_16x16x32_bf16 v[18:21], v[164:167], v[206:209], 0
	v_mfma_f32_16x16x32_bf16 v[22:25], v[172:175], v[206:209], 0
	v_mfma_f32_16x16x32_bf16 v[2:5], v[164:167], v[214:217], 0
	v_mfma_f32_16x16x32_bf16 v[6:9], v[172:175], v[214:217], 0
	v_mfma_f32_16x16x32_bf16 v[30:33], v[164:167], v[180:183], 0
	v_mfma_f32_16x16x32_bf16 v[38:41], v[172:175], v[180:183], 0
	v_mfma_f32_16x16x32_bf16 v[42:45], v[164:167], v[188:191], 0
	v_mfma_f32_16x16x32_bf16 v[46:49], v[172:175], v[188:191], 0
	v_mfma_f32_16x16x32_bf16 v[18:21], v[168:171], v[210:213], v[18:21]
	v_mfma_f32_16x16x32_bf16 v[22:25], v[176:179], v[210:213], v[22:25]
	v_mfma_f32_16x16x32_bf16 v[2:5], v[168:171], v[218:221], v[2:5]
	v_mfma_f32_16x16x32_bf16 v[6:9], v[176:179], v[218:221], v[6:9]
	v_mfma_f32_16x16x32_bf16 v[30:33], v[168:171], v[184:187], v[30:33]
	v_mfma_f32_16x16x32_bf16 v[38:41], v[176:179], v[184:187], v[38:41]
	v_mfma_f32_16x16x32_bf16 v[42:45], v[168:171], v[192:195], v[42:45]
	v_mfma_f32_16x16x32_bf16 v[50:53], v[176:179], v[192:195], v[46:49]
	s_barrier
	s_add_i32 s63, 0, 0x18000
	s_add_i32 s82, 0, 0x1c000
	v_add_u32_e32 v70, s63, v196
	v_add_u32_e32 v155, s82, v196
	ds_read_b128 v[46:49], v70
	ds_read_b128 v[54:57], v70 offset:1024
	ds_read_b128 v[66:69], v70 offset:2048
	ds_read_b128 v[70:73], v70 offset:3072
	ds_read_b128 v[164:167], v155
	ds_read_b128 v[168:171], v155 offset:1024
	ds_read_b128 v[172:175], v155 offset:2048
	ds_read_b128 v[176:179], v155 offset:3072
	s_add_u32 s68, s68, 0x100000
	s_addc_u32 s69, s69, 0
	s_mov_b32 m0, s43
	v_lshl_add_u64 v[230:231], s[68:69], 0, v[146:147]
	ds_read_b128 v[180:183], v202 offset:32768
	ds_read_b128 v[184:187], v202 offset:33792
	ds_read_b128 v[188:191], v202 offset:34816
	ds_read_b128 v[192:195], v202 offset:35840
	ds_read_b128 v[206:209], v202 offset:36864
	ds_read_b128 v[210:213], v202 offset:37888
	ds_read_b128 v[214:217], v202 offset:38912
	ds_read_b128 v[218:221], v202 offset:39936
	global_load_lds_dwordx4 v[230:231], off
	v_lshl_add_u64 v[230:231], s[68:69], 0, v[150:151]
	s_mov_b32 m0, s57
	s_nop 0
	global_load_lds_dwordx4 v[230:231], off
	s_waitcnt vmcnt(8)
	s_waitcnt lgkmcnt(0)
	s_barrier
	s_waitcnt lgkmcnt(0)
	v_mfma_f32_16x16x32_bf16 v[138:141], v[46:49], v[180:183], v[138:141]
	v_mfma_f32_16x16x32_bf16 v[142:145], v[66:69], v[180:183], v[142:145]
	v_mfma_f32_16x16x32_bf16 v[122:125], v[46:49], v[188:191], v[122:125]
	v_mfma_f32_16x16x32_bf16 v[126:129], v[66:69], v[188:191], v[126:129]
	v_mfma_f32_16x16x32_bf16 v[106:109], v[46:49], v[206:209], v[106:109]
	v_mfma_f32_16x16x32_bf16 v[110:113], v[66:69], v[206:209], v[110:113]
	v_mfma_f32_16x16x32_bf16 v[90:93], v[46:49], v[214:217], v[90:93]
	v_mfma_f32_16x16x32_bf16 v[94:97], v[66:69], v[214:217], v[94:97]
	v_mfma_f32_16x16x32_bf16 v[138:141], v[54:57], v[184:187], v[138:141]
	v_mfma_f32_16x16x32_bf16 v[142:145], v[70:73], v[184:187], v[142:145]
	v_mfma_f32_16x16x32_bf16 v[122:125], v[54:57], v[192:195], v[122:125]
	v_mfma_f32_16x16x32_bf16 v[126:129], v[70:73], v[192:195], v[126:129]
	v_mfma_f32_16x16x32_bf16 v[106:109], v[54:57], v[210:213], v[106:109]
	v_mfma_f32_16x16x32_bf16 v[110:113], v[70:73], v[210:213], v[110:113]
	v_mfma_f32_16x16x32_bf16 v[90:93], v[54:57], v[218:221], v[90:93]
	v_mfma_f32_16x16x32_bf16 v[94:97], v[70:73], v[218:221], v[94:97]
	v_mfma_f32_16x16x32_bf16 v[130:133], v[164:167], v[180:183], v[130:133]
	v_mfma_f32_16x16x32_bf16 v[134:137], v[172:175], v[180:183], v[134:137]
	v_mfma_f32_16x16x32_bf16 v[114:117], v[164:167], v[188:191], v[114:117]
	v_mfma_f32_16x16x32_bf16 v[118:121], v[172:175], v[188:191], v[118:121]
	v_mfma_f32_16x16x32_bf16 v[98:101], v[164:167], v[206:209], v[98:101]
	v_mfma_f32_16x16x32_bf16 v[102:105], v[172:175], v[206:209], v[102:105]
	v_mfma_f32_16x16x32_bf16 v[82:85], v[164:167], v[214:217], v[82:85]
	v_mfma_f32_16x16x32_bf16 v[86:89], v[172:175], v[214:217], v[86:89]
	v_mfma_f32_16x16x32_bf16 v[130:133], v[168:171], v[184:187], v[130:133]
	v_mfma_f32_16x16x32_bf16 v[134:137], v[176:179], v[184:187], v[134:137]
	v_mfma_f32_16x16x32_bf16 v[114:117], v[168:171], v[192:195], v[114:117]
	v_mfma_f32_16x16x32_bf16 v[118:121], v[176:179], v[192:195], v[118:121]
	v_mfma_f32_16x16x32_bf16 v[98:101], v[168:171], v[210:213], v[98:101]
	v_mfma_f32_16x16x32_bf16 v[102:105], v[176:179], v[210:213], v[102:105]
	v_mfma_f32_16x16x32_bf16 v[82:85], v[168:171], v[218:221], v[82:85]
	v_mfma_f32_16x16x32_bf16 v[86:89], v[176:179], v[218:221], v[86:89]
	s_barrier
	s_add_i32 s63, s63, s37
	v_lshl_add_u64 v[222:223], v[222:223], 0, s[26:27]
	s_mov_b32 m0, s63
	ds_read_b128 v[180:183], v202 offset:49152
	ds_read_b128 v[184:187], v202 offset:50176
	ds_read_b128 v[188:191], v202 offset:51200
	ds_read_b128 v[192:195], v202 offset:52224
	ds_read_b128 v[206:209], v202 offset:53248
	ds_read_b128 v[210:213], v202 offset:54272
	ds_read_b128 v[214:217], v202 offset:55296
	ds_read_b128 v[218:221], v202 offset:56320
	global_load_lds_dwordx4 v[222:223], off
	s_add_i32 m0, s63, 0x2000
	s_add_u32 s18, s18, 0x100080
	v_lshl_add_u64 v[222:223], v[224:225], 0, s[26:27]
	s_addc_u32 s19, s19, 0
	s_add_i32 s63, s82, s37
	global_load_lds_dwordx4 v[222:223], off
	v_lshl_add_u64 v[222:223], s[18:19], 0, v[148:149]
	s_mov_b32 m0, s63
	s_nop 0
	global_load_lds_dwordx4 v[222:223], off
	v_lshl_add_u64 v[222:223], s[18:19], 0, v[152:153]
	s_add_i32 m0, s63, 0x2000
	s_nop 0
	global_load_lds_dwordx4 v[222:223], off
	v_lshl_add_u64 v[222:223], v[226:227], 0, s[26:27]
	s_mov_b32 m0, s71
	s_nop 0
	global_load_lds_dwordx4 v[222:223], off
	v_lshl_add_u64 v[222:223], v[228:229], 0, s[26:27]
	s_mov_b32 m0, s72
	s_nop 0
	global_load_lds_dwordx4 v[222:223], off
	s_waitcnt vmcnt(8)
	s_waitcnt lgkmcnt(0)
	s_barrier
	s_waitcnt lgkmcnt(0)
	v_mfma_f32_16x16x32_bf16 v[74:77], v[46:49], v[180:183], v[74:77]
	v_mfma_f32_16x16x32_bf16 v[78:81], v[66:69], v[180:183], v[78:81]
	v_mfma_f32_16x16x32_bf16 v[58:61], v[46:49], v[188:191], v[58:61]
	v_mfma_f32_16x16x32_bf16 v[62:65], v[66:69], v[188:191], v[62:65]
	v_mfma_f32_16x16x32_bf16 v[26:29], v[46:49], v[206:209], v[26:29]
	v_mfma_f32_16x16x32_bf16 v[34:37], v[66:69], v[206:209], v[34:37]
	v_mfma_f32_16x16x32_bf16 v[10:13], v[46:49], v[214:217], v[10:13]
	v_mfma_f32_16x16x32_bf16 v[14:17], v[66:69], v[214:217], v[14:17]
	v_mfma_f32_16x16x32_bf16 v[74:77], v[54:57], v[184:187], v[74:77]
	v_mfma_f32_16x16x32_bf16 v[78:81], v[70:73], v[184:187], v[78:81]
	v_mfma_f32_16x16x32_bf16 v[58:61], v[54:57], v[192:195], v[58:61]
	v_mfma_f32_16x16x32_bf16 v[62:65], v[70:73], v[192:195], v[62:65]
	v_mfma_f32_16x16x32_bf16 v[26:29], v[54:57], v[210:213], v[26:29]
	v_mfma_f32_16x16x32_bf16 v[34:37], v[70:73], v[210:213], v[34:37]
	v_mfma_f32_16x16x32_bf16 v[10:13], v[54:57], v[218:221], v[10:13]
	v_mfma_f32_16x16x32_bf16 v[14:17], v[70:73], v[218:221], v[14:17]
	v_mfma_f32_16x16x32_bf16 v[30:33], v[164:167], v[180:183], v[30:33]
	v_mfma_f32_16x16x32_bf16 v[66:69], v[168:171], v[184:187], v[30:33]
	v_mfma_f32_16x16x32_bf16 v[30:33], v[172:175], v[180:183], v[38:41]
	v_mfma_f32_16x16x32_bf16 v[70:73], v[176:179], v[184:187], v[30:33]
	v_mfma_f32_16x16x32_bf16 v[30:33], v[164:167], v[188:191], v[42:45]
	v_mfma_f32_16x16x32_bf16 v[46:49], v[168:171], v[192:195], v[30:33]
	v_mfma_f32_16x16x32_bf16 v[30:33], v[172:175], v[188:191], v[50:53]
	v_mfma_f32_16x16x32_bf16 v[18:21], v[164:167], v[206:209], v[18:21]
	v_mfma_f32_16x16x32_bf16 v[22:25], v[172:175], v[206:209], v[22:25]
	v_mfma_f32_16x16x32_bf16 v[2:5], v[164:167], v[214:217], v[2:5]
	v_mfma_f32_16x16x32_bf16 v[6:9], v[172:175], v[214:217], v[6:9]
	v_mfma_f32_16x16x32_bf16 v[54:57], v[176:179], v[192:195], v[30:33]
	v_mfma_f32_16x16x32_bf16 v[18:21], v[168:171], v[210:213], v[18:21]
	v_mfma_f32_16x16x32_bf16 v[22:25], v[176:179], v[210:213], v[22:25]
	v_mfma_f32_16x16x32_bf16 v[2:5], v[168:171], v[218:221], v[2:5]
	v_mfma_f32_16x16x32_bf16 v[6:9], v[176:179], v[218:221], v[6:9]
	s_barrier
	s_add_i32 s61, s61, 2
	s_add_u32 s10, s10, 0x100
	s_addc_u32 s11, s11, 0
	s_add_u32 s16, s16, 0x100
	s_addc_u32 s17, s17, 0
	s_cmp_gt_u32 s61, 61

.LBB0_1920:
	s_ashr_i32 s31, s30, 31
	s_lshl_b64 s[34:35], s[30:31], 21
	s_add_u32 s34, s54, s34
	s_addc_u32 s35, s55, s35
	s_and_b64 s[36:37], s[2:3], exec
	s_cselect_b32 s31, s35, s39
	s_cselect_b32 s69, s34, s38
	s_ashr_i32 s29, s28, 31
	s_lshl_b64 s[36:37], s[28:29], 21
	s_add_u32 s36, s1, s36
	s_addc_u32 s37, s16, s37
	s_and_b64 s[42:43], s[2:3], exec
	s_cselect_b32 s29, s37, s41
	s_cselect_b32 s70, s36, s40
	s_add_u32 s38, s38, 0x100080
	s_addc_u32 s39, s39, 0
	s_add_u32 s71, s40, 0x100
	s_addc_u32 s72, s41, 0
	s_mov_b32 s73, -2
	ds_read_b128 v[130:133], v212
	ds_read_b128 v[134:137], v212 offset:1024
	ds_read_b128 v[138:141], v212 offset:2048
	ds_read_b128 v[142:145], v212 offset:3072
	ds_read_b128 v[146:149], v213
	ds_read_b128 v[150:153], v213 offset:1024
	ds_read_b128 v[154:157], v213 offset:2048
	ds_read_b128 v[158:161], v213 offset:3072
	s_add_u32 s40, s38, 0xfff00080
	s_addc_u32 s41, s39, -1
	s_cmp_eq_u32 s73, 60
	s_cselect_b32 s43, s31, s41
	s_cselect_b32 s42, s69, s40
	s_cselect_b32 s41, s29, s72
	s_cselect_b32 s40, s70, s71
	v_lshl_add_u64 v[216:217], s[38:39], 0, v[178:179]
	s_add_i32 m0, s19, 0xc000
	ds_read_b128 v[162:165], v214
	ds_read_b128 v[166:169], v214 offset:1024
	ds_read_b128 v[186:189], v214 offset:2048
	ds_read_b128 v[190:193], v214 offset:3072
	ds_read_b128 v[194:197], v214 offset:4096
	ds_read_b128 v[198:201], v214 offset:5120
	ds_read_b128 v[202:205], v214 offset:6144
	ds_read_b128 v[206:209], v214 offset:7168
	global_load_lds_dwordx4 v[216:217], off
	v_lshl_add_u64 v[216:217], s[38:39], 0, v[180:181]
	s_add_i32 m0, s19, 0xe000
	s_nop 0
	global_load_lds_dwordx4 v[216:217], off
	s_waitcnt vmcnt(8)
	s_waitcnt lgkmcnt(0)
	s_barrier
	s_waitcnt lgkmcnt(0)
	v_mfma_f32_16x16x32_bf16 v[126:129], v[130:133], v[162:165], 0
	v_mfma_f32_16x16x32_bf16 v[122:125], v[138:141], v[162:165], 0
	v_mfma_f32_16x16x32_bf16 v[110:113], v[130:133], v[186:189], 0
	v_mfma_f32_16x16x32_bf16 v[106:109], v[138:141], v[186:189], 0
	v_mfma_f32_16x16x32_bf16 v[94:97], v[130:133], v[194:197], 0
	v_mfma_f32_16x16x32_bf16 v[90:93], v[138:141], v[194:197], 0
	v_mfma_f32_16x16x32_bf16 v[78:81], v[130:133], v[202:205], 0
	v_mfma_f32_16x16x32_bf16 v[74:77], v[138:141], v[202:205], 0
	v_mfma_f32_16x16x32_bf16 v[126:129], v[134:137], v[166:169], v[126:129]
	v_mfma_f32_16x16x32_bf16 v[122:125], v[142:145], v[166:169], v[122:125]
	v_mfma_f32_16x16x32_bf16 v[110:113], v[134:137], v[190:193], v[110:113]
	v_mfma_f32_16x16x32_bf16 v[106:109], v[142:145], v[190:193], v[106:109]
	v_mfma_f32_16x16x32_bf16 v[94:97], v[134:137], v[198:201], v[94:97]
	v_mfma_f32_16x16x32_bf16 v[90:93], v[142:145], v[198:201], v[90:93]
	v_mfma_f32_16x16x32_bf16 v[78:81], v[134:137], v[206:209], v[78:81]
	v_mfma_f32_16x16x32_bf16 v[74:77], v[142:145], v[206:209], v[74:77]
	v_mfma_f32_16x16x32_bf16 v[118:121], v[146:149], v[162:165], 0
	v_mfma_f32_16x16x32_bf16 v[114:117], v[154:157], v[162:165], 0
	v_mfma_f32_16x16x32_bf16 v[102:105], v[146:149], v[186:189], 0
	v_mfma_f32_16x16x32_bf16 v[98:101], v[154:157], v[186:189], 0
	v_mfma_f32_16x16x32_bf16 v[86:89], v[146:149], v[194:197], 0
	v_mfma_f32_16x16x32_bf16 v[82:85], v[154:157], v[194:197], 0
	v_mfma_f32_16x16x32_bf16 v[70:73], v[146:149], v[202:205], 0
	v_mfma_f32_16x16x32_bf16 v[66:69], v[154:157], v[202:205], 0
	v_mfma_f32_16x16x32_bf16 v[118:121], v[150:153], v[166:169], v[118:121]
	v_mfma_f32_16x16x32_bf16 v[114:117], v[158:161], v[166:169], v[114:117]
	v_mfma_f32_16x16x32_bf16 v[102:105], v[150:153], v[190:193], v[102:105]
	v_mfma_f32_16x16x32_bf16 v[98:101], v[158:161], v[190:193], v[98:101]
	v_mfma_f32_16x16x32_bf16 v[86:89], v[150:153], v[198:201], v[86:89]
	v_mfma_f32_16x16x32_bf16 v[82:85], v[158:161], v[198:201], v[82:85]
	v_mfma_f32_16x16x32_bf16 v[70:73], v[150:153], v[206:209], v[70:73]
	v_mfma_f32_16x16x32_bf16 v[66:69], v[158:161], v[206:209], v[66:69]
	s_barrier
	s_add_i32 s76, s57, s17
	v_lshl_add_u64 v[216:217], s[40:41], 0, v[172:173]
	s_mov_b32 m0, s76
	ds_read_b128 v[162:165], v214 offset:16384
	ds_read_b128 v[166:169], v214 offset:17408
	ds_read_b128 v[186:189], v214 offset:18432
	ds_read_b128 v[190:193], v214 offset:19456
	ds_read_b128 v[194:197], v214 offset:20480
	ds_read_b128 v[198:201], v214 offset:21504
	ds_read_b128 v[202:205], v214 offset:22528
	ds_read_b128 v[206:209], v214 offset:23552
	global_load_lds_dwordx4 v[216:217], off
	s_add_i32 m0, s76, 0x2000
	s_add_u32 s76, s40, 0x100000
	v_lshl_add_u64 v[218:219], s[40:41], 0, v[176:177]
	s_addc_u32 s77, s41, 0
	s_add_i32 s78, s60, s17
	global_load_lds_dwordx4 v[218:219], off
	v_lshl_add_u64 v[220:221], s[76:77], 0, v[172:173]
	s_mov_b32 m0, s78
	v_lshl_add_u64 v[222:223], s[42:43], 0, v[174:175]
	global_load_lds_dwordx4 v[220:221], off
	v_lshl_add_u64 v[220:221], s[76:77], 0, v[176:177]
	s_add_i32 m0, s78, 0x2000
	s_nop 0
	global_load_lds_dwordx4 v[220:221], off
	v_lshl_add_u64 v[220:221], s[42:43], 0, v[170:171]
	s_mov_b32 m0, s19
	s_nop 0
	global_load_lds_dwordx4 v[220:221], off
	s_mov_b32 m0, s44
	s_nop 0
	global_load_lds_dwordx4 v[222:223], off
	s_waitcnt vmcnt(8)
	s_waitcnt lgkmcnt(0)
	s_barrier
	s_waitcnt lgkmcnt(0)
	v_mfma_f32_16x16x32_bf16 v[62:65], v[130:133], v[162:165], 0
	v_mfma_f32_16x16x32_bf16 v[58:61], v[138:141], v[162:165], 0
	v_mfma_f32_16x16x32_bf16 v[46:49], v[130:133], v[186:189], 0
	v_mfma_f32_16x16x32_bf16 v[42:45], v[138:141], v[186:189], 0
	v_mfma_f32_16x16x32_bf16 v[30:33], v[130:133], v[194:197], 0
	v_mfma_f32_16x16x32_bf16 v[26:29], v[138:141], v[194:197], 0
	v_mfma_f32_16x16x32_bf16 v[14:17], v[130:133], v[202:205], 0
	v_mfma_f32_16x16x32_bf16 v[10:13], v[138:141], v[202:205], 0
	v_mfma_f32_16x16x32_bf16 v[62:65], v[134:137], v[166:169], v[62:65]
	v_mfma_f32_16x16x32_bf16 v[58:61], v[142:145], v[166:169], v[58:61]
	v_mfma_f32_16x16x32_bf16 v[46:49], v[134:137], v[190:193], v[46:49]
	v_mfma_f32_16x16x32_bf16 v[42:45], v[142:145], v[190:193], v[42:45]
	v_mfma_f32_16x16x32_bf16 v[30:33], v[134:137], v[198:201], v[30:33]
	v_mfma_f32_16x16x32_bf16 v[26:29], v[142:145], v[198:201], v[26:29]
	v_mfma_f32_16x16x32_bf16 v[14:17], v[134:137], v[206:209], v[14:17]
	v_mfma_f32_16x16x32_bf16 v[10:13], v[142:145], v[206:209], v[10:13]
	v_mfma_f32_16x16x32_bf16 v[54:57], v[146:149], v[162:165], 0
	v_mfma_f32_16x16x32_bf16 v[50:53], v[154:157], v[162:165], 0
	v_mfma_f32_16x16x32_bf16 v[38:41], v[146:149], v[186:189], 0
	v_mfma_f32_16x16x32_bf16 v[34:37], v[154:157], v[186:189], 0
	v_mfma_f32_16x16x32_bf16 v[22:25], v[146:149], v[194:197], 0
	v_mfma_f32_16x16x32_bf16 v[18:21], v[154:157], v[194:197], 0
	v_mfma_f32_16x16x32_bf16 v[6:9], v[146:149], v[202:205], 0
	v_mfma_f32_16x16x32_bf16 v[2:5], v[154:157], v[202:205], 0
	v_mfma_f32_16x16x32_bf16 v[54:57], v[150:153], v[166:169], v[54:57]
	v_mfma_f32_16x16x32_bf16 v[50:53], v[158:161], v[166:169], v[50:53]
	v_mfma_f32_16x16x32_bf16 v[38:41], v[150:153], v[190:193], v[38:41]
	v_mfma_f32_16x16x32_bf16 v[34:37], v[158:161], v[190:193], v[34:37]
	v_mfma_f32_16x16x32_bf16 v[22:25], v[150:153], v[198:201], v[22:25]
	v_mfma_f32_16x16x32_bf16 v[18:21], v[158:161], v[198:201], v[18:21]
	v_mfma_f32_16x16x32_bf16 v[6:9], v[150:153], v[206:209], v[6:9]
	v_mfma_f32_16x16x32_bf16 v[2:5], v[158:161], v[206:209], v[2:5]
	s_barrier
	s_add_i32 s76, 0, 0x18000
	s_add_i32 s77, 0, 0x1c000
	v_add_u32_e32 v142, s76, v211
	v_add_u32_e32 v158, s77, v211
	ds_read_b128 v[130:133], v142
	ds_read_b128 v[134:137], v142 offset:1024
	ds_read_b128 v[138:141], v142 offset:2048
	ds_read_b128 v[142:145], v142 offset:3072
	ds_read_b128 v[146:149], v158
	ds_read_b128 v[150:153], v158 offset:1024
	ds_read_b128 v[154:157], v158 offset:2048
	ds_read_b128 v[158:161], v158 offset:3072
	s_add_u32 s42, s42, 0x100000
	s_addc_u32 s43, s43, 0
	s_mov_b32 m0, s45
	v_lshl_add_u64 v[224:225], s[42:43], 0, v[170:171]
	ds_read_b128 v[162:165], v214 offset:32768
	ds_read_b128 v[166:169], v214 offset:33792
	ds_read_b128 v[186:189], v214 offset:34816
	ds_read_b128 v[190:193], v214 offset:35840
	ds_read_b128 v[194:197], v214 offset:36864
	ds_read_b128 v[198:201], v214 offset:37888
	ds_read_b128 v[202:205], v214 offset:38912
	ds_read_b128 v[206:209], v214 offset:39936
	global_load_lds_dwordx4 v[224:225], off
	v_lshl_add_u64 v[224:225], s[42:43], 0, v[174:175]
	s_mov_b32 m0, s46
	s_nop 0
	global_load_lds_dwordx4 v[224:225], off
	s_waitcnt vmcnt(8)
	s_waitcnt lgkmcnt(0)
	s_barrier
	s_waitcnt lgkmcnt(0)
	v_mfma_f32_16x16x32_bf16 v[126:129], v[130:133], v[162:165], v[126:129]
	v_mfma_f32_16x16x32_bf16 v[122:125], v[138:141], v[162:165], v[122:125]
	v_mfma_f32_16x16x32_bf16 v[110:113], v[130:133], v[186:189], v[110:113]
	v_mfma_f32_16x16x32_bf16 v[106:109], v[138:141], v[186:189], v[106:109]
	v_mfma_f32_16x16x32_bf16 v[94:97], v[130:133], v[194:197], v[94:97]
	v_mfma_f32_16x16x32_bf16 v[90:93], v[138:141], v[194:197], v[90:93]
	v_mfma_f32_16x16x32_bf16 v[78:81], v[130:133], v[202:205], v[78:81]
	v_mfma_f32_16x16x32_bf16 v[74:77], v[138:141], v[202:205], v[74:77]
	v_mfma_f32_16x16x32_bf16 v[126:129], v[134:137], v[166:169], v[126:129]
	v_mfma_f32_16x16x32_bf16 v[122:125], v[142:145], v[166:169], v[122:125]
	v_mfma_f32_16x16x32_bf16 v[110:113], v[134:137], v[190:193], v[110:113]
	v_mfma_f32_16x16x32_bf16 v[106:109], v[142:145], v[190:193], v[106:109]
	v_mfma_f32_16x16x32_bf16 v[94:97], v[134:137], v[198:201], v[94:97]
	v_mfma_f32_16x16x32_bf16 v[90:93], v[142:145], v[198:201], v[90:93]
	v_mfma_f32_16x16x32_bf16 v[78:81], v[134:137], v[206:209], v[78:81]
	v_mfma_f32_16x16x32_bf16 v[74:77], v[142:145], v[206:209], v[74:77]
	v_mfma_f32_16x16x32_bf16 v[118:121], v[146:149], v[162:165], v[118:121]
	v_mfma_f32_16x16x32_bf16 v[114:117], v[154:157], v[162:165], v[114:117]
	v_mfma_f32_16x16x32_bf16 v[102:105], v[146:149], v[186:189], v[102:105]
	v_mfma_f32_16x16x32_bf16 v[98:101], v[154:157], v[186:189], v[98:101]
	v_mfma_f32_16x16x32_bf16 v[86:89], v[146:149], v[194:197], v[86:89]
	v_mfma_f32_16x16x32_bf16 v[82:85], v[154:157], v[194:197], v[82:85]
	v_mfma_f32_16x16x32_bf16 v[70:73], v[146:149], v[202:205], v[70:73]
	v_mfma_f32_16x16x32_bf16 v[66:69], v[154:157], v[202:205], v[66:69]
	v_mfma_f32_16x16x32_bf16 v[118:121], v[150:153], v[166:169], v[118:121]
	v_mfma_f32_16x16x32_bf16 v[114:117], v[158:161], v[166:169], v[114:117]
	v_mfma_f32_16x16x32_bf16 v[102:105], v[150:153], v[190:193], v[102:105]
	v_mfma_f32_16x16x32_bf16 v[98:101], v[158:161], v[190:193], v[98:101]
	v_mfma_f32_16x16x32_bf16 v[86:89], v[150:153], v[198:201], v[86:89]
	v_mfma_f32_16x16x32_bf16 v[82:85], v[158:161], v[198:201], v[82:85]
	v_mfma_f32_16x16x32_bf16 v[70:73], v[150:153], v[206:209], v[70:73]
	v_mfma_f32_16x16x32_bf16 v[66:69], v[158:161], v[206:209], v[66:69]
	s_barrier
	s_add_i32 s42, s76, s17
	v_lshl_add_u64 v[216:217], v[216:217], 0, s[8:9]
	s_mov_b32 m0, s42
	ds_read_b128 v[162:165], v214 offset:49152
	ds_read_b128 v[166:169], v214 offset:50176
	ds_read_b128 v[186:189], v214 offset:51200
	ds_read_b128 v[190:193], v214 offset:52224
	ds_read_b128 v[194:197], v214 offset:53248
	ds_read_b128 v[198:201], v214 offset:54272
	ds_read_b128 v[202:205], v214 offset:55296
	ds_read_b128 v[206:209], v214 offset:56320
	global_load_lds_dwordx4 v[216:217], off
	s_add_i32 m0, s42, 0x2000
	s_add_u32 s40, s40, 0x100080
	v_lshl_add_u64 v[216:217], v[218:219], 0, s[8:9]
	s_addc_u32 s41, s41, 0
	s_add_i32 s42, s77, s17
	global_load_lds_dwordx4 v[216:217], off
	v_lshl_add_u64 v[216:217], s[40:41], 0, v[172:173]
	s_mov_b32 m0, s42
	s_nop 0
	global_load_lds_dwordx4 v[216:217], off
	v_lshl_add_u64 v[216:217], s[40:41], 0, v[176:177]
	s_add_i32 m0, s42, 0x2000
	s_nop 0
	global_load_lds_dwordx4 v[216:217], off
	v_lshl_add_u64 v[216:217], v[220:221], 0, s[8:9]
	s_mov_b32 m0, s50
	s_nop 0
	global_load_lds_dwordx4 v[216:217], off
	v_lshl_add_u64 v[216:217], v[222:223], 0, s[8:9]
	s_mov_b32 m0, s51
	s_nop 0
	global_load_lds_dwordx4 v[216:217], off
	s_waitcnt vmcnt(8)
	s_waitcnt lgkmcnt(0)
	s_barrier
	s_waitcnt lgkmcnt(0)
	v_mfma_f32_16x16x32_bf16 v[62:65], v[130:133], v[162:165], v[62:65]
	v_mfma_f32_16x16x32_bf16 v[58:61], v[138:141], v[162:165], v[58:61]
	v_mfma_f32_16x16x32_bf16 v[46:49], v[130:133], v[186:189], v[46:49]
	v_mfma_f32_16x16x32_bf16 v[42:45], v[138:141], v[186:189], v[42:45]
	v_mfma_f32_16x16x32_bf16 v[30:33], v[130:133], v[194:197], v[30:33]
	v_mfma_f32_16x16x32_bf16 v[26:29], v[138:141], v[194:197], v[26:29]
	v_mfma_f32_16x16x32_bf16 v[14:17], v[130:133], v[202:205], v[14:17]
	v_mfma_f32_16x16x32_bf16 v[10:13], v[138:141], v[202:205], v[10:13]
	v_mfma_f32_16x16x32_bf16 v[62:65], v[134:137], v[166:169], v[62:65]
	v_mfma_f32_16x16x32_bf16 v[58:61], v[142:145], v[166:169], v[58:61]
	v_mfma_f32_16x16x32_bf16 v[46:49], v[134:137], v[190:193], v[46:49]
	v_mfma_f32_16x16x32_bf16 v[42:45], v[142:145], v[190:193], v[42:45]
	v_mfma_f32_16x16x32_bf16 v[30:33], v[134:137], v[198:201], v[30:33]
	v_mfma_f32_16x16x32_bf16 v[26:29], v[142:145], v[198:201], v[26:29]
	v_mfma_f32_16x16x32_bf16 v[14:17], v[134:137], v[206:209], v[14:17]
	v_mfma_f32_16x16x32_bf16 v[10:13], v[142:145], v[206:209], v[10:13]
	v_mfma_f32_16x16x32_bf16 v[54:57], v[146:149], v[162:165], v[54:57]
	v_mfma_f32_16x16x32_bf16 v[50:53], v[154:157], v[162:165], v[50:53]
	v_mfma_f32_16x16x32_bf16 v[38:41], v[146:149], v[186:189], v[38:41]
	v_mfma_f32_16x16x32_bf16 v[34:37], v[154:157], v[186:189], v[34:37]
	v_mfma_f32_16x16x32_bf16 v[22:25], v[146:149], v[194:197], v[22:25]
	v_mfma_f32_16x16x32_bf16 v[18:21], v[154:157], v[194:197], v[18:21]
	v_mfma_f32_16x16x32_bf16 v[6:9], v[146:149], v[202:205], v[6:9]
	v_mfma_f32_16x16x32_bf16 v[2:5], v[154:157], v[202:205], v[2:5]
	v_mfma_f32_16x16x32_bf16 v[54:57], v[150:153], v[166:169], v[54:57]
	v_mfma_f32_16x16x32_bf16 v[50:53], v[158:161], v[166:169], v[50:53]
	v_mfma_f32_16x16x32_bf16 v[38:41], v[150:153], v[190:193], v[38:41]
	v_mfma_f32_16x16x32_bf16 v[34:37], v[158:161], v[190:193], v[34:37]
	v_mfma_f32_16x16x32_bf16 v[22:25], v[150:153], v[198:201], v[22:25]
	v_mfma_f32_16x16x32_bf16 v[18:21], v[158:161], v[198:201], v[18:21]
	v_mfma_f32_16x16x32_bf16 v[6:9], v[150:153], v[206:209], v[6:9]
	v_mfma_f32_16x16x32_bf16 v[2:5], v[158:161], v[206:209], v[2:5]
	s_barrier
	s_add_i32 s73, s73, 2
	s_add_u32 s38, s38, 0x100
	s_addc_u32 s39, s39, 0
	s_add_u32 s71, s71, 0x100
	s_addc_u32 s72, s72, 0
	s_cmp_gt_u32 s73, 61

.LBB0_2055:
	s_ashr_i32 s31, s30, 31
	s_lshl_b64 s[18:19], s[30:31], 20
	s_add_u32 s34, s27, s18
	s_addc_u32 s35, s44, s19
	s_and_b64 s[18:19], s[0:1], exec
	s_cselect_b32 s31, s35, s3
	s_cselect_b32 s87, s34, s2
	s_ashr_i32 s29, s28, 31
	s_lshl_b64 s[18:19], s[28:29], 20
	s_add_u32 s36, s45, s18
	s_addc_u32 s37, s46, s19
	s_and_b64 s[18:19], s[0:1], exec
	s_cselect_b32 s29, s37, s5
	s_cselect_b32 s90, s36, s4
	s_add_u32 s91, s4, 0x100
	s_addc_u32 s92, s5, 0
	s_mov_b32 s93, -2
	ds_read_b128 v[130:133], v234
	ds_read_b128 v[134:137], v234 offset:1024
	ds_read_b128 v[162:165], v234 offset:2048
	ds_read_b128 v[166:169], v234 offset:3072
	ds_read_b128 v[170:173], v235
	ds_read_b128 v[174:177], v235 offset:1024
	ds_read_b128 v[178:181], v235 offset:2048
	ds_read_b128 v[182:185], v235 offset:3072
	s_add_u32 s4, s2, 0x100
	s_addc_u32 s5, s3, 0
	s_cmp_eq_u32 s93, 28
	s_cselect_b32 s43, s31, s5
	s_cselect_b32 s42, s87, s4
	s_cselect_b32 s19, s29, s92
	s_cselect_b32 s18, s90, s91
	v_lshl_add_u64 v[218:219], s[2:3], 0, v[154:155]
	s_add_i32 m0, s49, 0xc000
	ds_read_b128 v[186:189], v236
	ds_read_b128 v[190:193], v236 offset:1024
	ds_read_b128 v[194:197], v236 offset:2048
	ds_read_b128 v[198:201], v236 offset:3072
	ds_read_b128 v[202:205], v236 offset:4096
	ds_read_b128 v[206:209], v236 offset:5120
	ds_read_b128 v[210:213], v236 offset:6144
	ds_read_b128 v[214:217], v236 offset:7168
	global_load_lds_dwordx4 v[218:219], off
	v_lshl_add_u64 v[218:219], s[2:3], 0, v[156:157]
	s_add_i32 m0, s49, 0xe000
	s_nop 0
	global_load_lds_dwordx4 v[218:219], off
	s_waitcnt vmcnt(8)
	s_waitcnt lgkmcnt(0)
	s_barrier
	s_waitcnt lgkmcnt(0)
	v_mfma_i32_16x16x64_i8 v[118:121], v[130:133], v[186:189], 0
	v_mfma_i32_16x16x64_i8 v[102:105], v[162:165], v[186:189], 0
	v_mfma_i32_16x16x64_i8 v[114:117], v[130:133], v[194:197], 0
	v_mfma_i32_16x16x64_i8 v[98:101], v[162:165], v[194:197], 0
	v_mfma_i32_16x16x64_i8 v[126:129], v[130:133], v[202:205], 0
	v_mfma_i32_16x16x64_i8 v[110:113], v[162:165], v[202:205], 0
	v_mfma_i32_16x16x64_i8 v[122:125], v[130:133], v[210:213], 0
	v_mfma_i32_16x16x64_i8 v[106:109], v[162:165], v[210:213], 0
	v_mfma_i32_16x16x64_i8 v[118:121], v[134:137], v[190:193], v[118:121]
	v_mfma_i32_16x16x64_i8 v[102:105], v[166:169], v[190:193], v[102:105]
	v_mfma_i32_16x16x64_i8 v[114:117], v[134:137], v[198:201], v[114:117]
	v_mfma_i32_16x16x64_i8 v[98:101], v[166:169], v[198:201], v[98:101]
	v_mfma_i32_16x16x64_i8 v[126:129], v[134:137], v[206:209], v[126:129]
	v_mfma_i32_16x16x64_i8 v[110:113], v[166:169], v[206:209], v[110:113]
	v_mfma_i32_16x16x64_i8 v[122:125], v[134:137], v[214:217], v[122:125]
	v_mfma_i32_16x16x64_i8 v[106:109], v[166:169], v[214:217], v[106:109]
	v_mfma_i32_16x16x64_i8 v[86:89], v[170:173], v[186:189], 0
	v_mfma_i32_16x16x64_i8 v[70:73], v[178:181], v[186:189], 0
	v_mfma_i32_16x16x64_i8 v[82:85], v[170:173], v[194:197], 0
	v_mfma_i32_16x16x64_i8 v[66:69], v[178:181], v[194:197], 0
	v_mfma_i32_16x16x64_i8 v[94:97], v[170:173], v[202:205], 0
	v_mfma_i32_16x16x64_i8 v[78:81], v[178:181], v[202:205], 0
	v_mfma_i32_16x16x64_i8 v[90:93], v[170:173], v[210:213], 0
	v_mfma_i32_16x16x64_i8 v[74:77], v[178:181], v[210:213], 0
	v_mfma_i32_16x16x64_i8 v[86:89], v[174:177], v[190:193], v[86:89]
	v_mfma_i32_16x16x64_i8 v[70:73], v[182:185], v[190:193], v[70:73]
	v_mfma_i32_16x16x64_i8 v[82:85], v[174:177], v[198:201], v[82:85]
	v_mfma_i32_16x16x64_i8 v[66:69], v[182:185], v[198:201], v[66:69]
	v_mfma_i32_16x16x64_i8 v[94:97], v[174:177], v[206:209], v[94:97]
	v_mfma_i32_16x16x64_i8 v[78:81], v[182:185], v[206:209], v[78:81]
	v_mfma_i32_16x16x64_i8 v[90:93], v[174:177], v[214:217], v[90:93]
	v_mfma_i32_16x16x64_i8 v[74:77], v[182:185], v[214:217], v[74:77]
	s_barrier
	s_add_i32 s2, s82, s47
	v_lshl_add_u64 v[218:219], s[18:19], 0, v[144:145]
	s_mov_b32 m0, s2
	ds_read_b128 v[186:189], v236 offset:16384
	ds_read_b128 v[190:193], v236 offset:17408
	ds_read_b128 v[194:197], v236 offset:18432
	ds_read_b128 v[198:201], v236 offset:19456
	ds_read_b128 v[202:205], v236 offset:20480
	ds_read_b128 v[206:209], v236 offset:21504
	ds_read_b128 v[210:213], v236 offset:22528
	ds_read_b128 v[214:217], v236 offset:23552
	global_load_lds_dwordx4 v[218:219], off
	s_add_i32 m0, s2, 0x2000
	s_add_u32 s2, s18, 0x80000
	v_lshl_add_u64 v[220:221], s[18:19], 0, v[148:149]
	s_addc_u32 s3, s19, 0
	s_add_i32 s94, s16, s47
	global_load_lds_dwordx4 v[220:221], off
	v_lshl_add_u64 v[222:223], s[2:3], 0, v[144:145]
	s_mov_b32 m0, s94
	v_lshl_add_u64 v[224:225], s[42:43], 0, v[146:147]
	global_load_lds_dwordx4 v[222:223], off
	v_lshl_add_u64 v[222:223], s[2:3], 0, v[148:149]
	s_add_i32 m0, s94, 0x2000
	s_nop 0
	global_load_lds_dwordx4 v[222:223], off
	v_lshl_add_u64 v[222:223], s[42:43], 0, v[142:143]
	s_mov_b32 m0, s49
	s_nop 0
	global_load_lds_dwordx4 v[222:223], off
	s_mov_b32 m0, s50
	s_nop 0
	global_load_lds_dwordx4 v[224:225], off
	s_waitcnt vmcnt(8)
	s_waitcnt lgkmcnt(0)
	s_barrier
	s_waitcnt lgkmcnt(0)
	v_mfma_i32_16x16x64_i8 v[54:57], v[130:133], v[186:189], 0
	v_mfma_i32_16x16x64_i8 v[18:21], v[162:165], v[186:189], 0
	v_mfma_i32_16x16x64_i8 v[50:53], v[130:133], v[194:197], 0
	v_mfma_i32_16x16x64_i8 v[22:25], v[162:165], v[194:197], 0
	v_mfma_i32_16x16x64_i8 v[62:65], v[130:133], v[202:205], 0
	v_mfma_i32_16x16x64_i8 v[30:33], v[162:165], v[202:205], 0
	v_mfma_i32_16x16x64_i8 v[58:61], v[130:133], v[210:213], 0
	v_mfma_i32_16x16x64_i8 v[26:29], v[162:165], v[210:213], 0
	v_mfma_i32_16x16x64_i8 v[54:57], v[134:137], v[190:193], v[54:57]
	v_mfma_i32_16x16x64_i8 v[18:21], v[166:169], v[190:193], v[18:21]
	v_mfma_i32_16x16x64_i8 v[50:53], v[134:137], v[198:201], v[50:53]
	v_mfma_i32_16x16x64_i8 v[22:25], v[166:169], v[198:201], v[22:25]
	v_mfma_i32_16x16x64_i8 v[62:65], v[134:137], v[206:209], v[62:65]
	v_mfma_i32_16x16x64_i8 v[30:33], v[166:169], v[206:209], v[30:33]
	v_mfma_i32_16x16x64_i8 v[58:61], v[134:137], v[214:217], v[58:61]
	v_mfma_i32_16x16x64_i8 v[26:29], v[166:169], v[214:217], v[26:29]
	v_mfma_i32_16x16x64_i8 v[46:49], v[170:173], v[186:189], 0
	v_mfma_i32_16x16x64_i8 v[14:17], v[178:181], v[186:189], 0
	v_mfma_i32_16x16x64_i8 v[42:45], v[170:173], v[194:197], 0
	v_mfma_i32_16x16x64_i8 v[10:13], v[178:181], v[194:197], 0
	v_mfma_i32_16x16x64_i8 v[38:41], v[170:173], v[202:205], 0
	v_mfma_i32_16x16x64_i8 v[6:9], v[178:181], v[202:205], 0
	v_mfma_i32_16x16x64_i8 v[34:37], v[170:173], v[210:213], 0
	v_mfma_i32_16x16x64_i8 v[2:5], v[178:181], v[210:213], 0
	v_mfma_i32_16x16x64_i8 v[46:49], v[174:177], v[190:193], v[46:49]
	v_mfma_i32_16x16x64_i8 v[14:17], v[182:185], v[190:193], v[14:17]
	v_mfma_i32_16x16x64_i8 v[42:45], v[174:177], v[198:201], v[42:45]
	v_mfma_i32_16x16x64_i8 v[10:13], v[182:185], v[198:201], v[10:13]
	v_mfma_i32_16x16x64_i8 v[38:41], v[174:177], v[206:209], v[38:41]
	v_mfma_i32_16x16x64_i8 v[6:9], v[182:185], v[206:209], v[6:9]
	v_mfma_i32_16x16x64_i8 v[34:37], v[174:177], v[214:217], v[34:37]
	v_mfma_i32_16x16x64_i8 v[2:5], v[182:185], v[214:217], v[2:5]
	s_barrier
	s_add_i32 s94, 0, 0x18000
	s_add_i32 s95, 0, 0x1c000
	v_add_u32_e32 v166, s94, v232
	v_add_u32_e32 v182, s95, v232
	ds_read_b128 v[130:133], v166
	ds_read_b128 v[134:137], v166 offset:1024
	ds_read_b128 v[162:165], v166 offset:2048
	ds_read_b128 v[166:169], v166 offset:3072
	ds_read_b128 v[170:173], v182
	ds_read_b128 v[174:177], v182 offset:1024
	ds_read_b128 v[178:181], v182 offset:2048
	ds_read_b128 v[182:185], v182 offset:3072
	s_add_u32 s2, s42, 0x80000
	s_addc_u32 s3, s43, 0
	s_mov_b32 m0, s51
	v_lshl_add_u64 v[226:227], s[2:3], 0, v[142:143]
	ds_read_b128 v[186:189], v236 offset:32768
	ds_read_b128 v[190:193], v236 offset:33792
	ds_read_b128 v[194:197], v236 offset:34816
	ds_read_b128 v[198:201], v236 offset:35840
	ds_read_b128 v[202:205], v236 offset:36864
	ds_read_b128 v[206:209], v236 offset:37888
	ds_read_b128 v[210:213], v236 offset:38912
	ds_read_b128 v[214:217], v236 offset:39936
	global_load_lds_dwordx4 v[226:227], off
	v_lshl_add_u64 v[226:227], s[2:3], 0, v[146:147]
	s_mov_b32 m0, s54
	s_nop 0
	global_load_lds_dwordx4 v[226:227], off
	s_waitcnt vmcnt(8)
	s_waitcnt lgkmcnt(0)
	s_barrier
	s_waitcnt lgkmcnt(0)
	v_mfma_i32_16x16x64_i8 v[118:121], v[130:133], v[186:189], v[118:121]
	v_mfma_i32_16x16x64_i8 v[102:105], v[162:165], v[186:189], v[102:105]
	v_mfma_i32_16x16x64_i8 v[114:117], v[130:133], v[194:197], v[114:117]
	v_mfma_i32_16x16x64_i8 v[98:101], v[162:165], v[194:197], v[98:101]
	v_mfma_i32_16x16x64_i8 v[126:129], v[130:133], v[202:205], v[126:129]
	v_mfma_i32_16x16x64_i8 v[110:113], v[162:165], v[202:205], v[110:113]
	v_mfma_i32_16x16x64_i8 v[122:125], v[130:133], v[210:213], v[122:125]
	v_mfma_i32_16x16x64_i8 v[106:109], v[162:165], v[210:213], v[106:109]
	v_mfma_i32_16x16x64_i8 v[118:121], v[134:137], v[190:193], v[118:121]
	v_mfma_i32_16x16x64_i8 v[102:105], v[166:169], v[190:193], v[102:105]
	v_mfma_i32_16x16x64_i8 v[114:117], v[134:137], v[198:201], v[114:117]
	v_mfma_i32_16x16x64_i8 v[98:101], v[166:169], v[198:201], v[98:101]
	v_mfma_i32_16x16x64_i8 v[126:129], v[134:137], v[206:209], v[126:129]
	v_mfma_i32_16x16x64_i8 v[110:113], v[166:169], v[206:209], v[110:113]
	v_mfma_i32_16x16x64_i8 v[122:125], v[134:137], v[214:217], v[122:125]
	v_mfma_i32_16x16x64_i8 v[106:109], v[166:169], v[214:217], v[106:109]
	v_mfma_i32_16x16x64_i8 v[86:89], v[170:173], v[186:189], v[86:89]
	v_mfma_i32_16x16x64_i8 v[70:73], v[178:181], v[186:189], v[70:73]
	v_mfma_i32_16x16x64_i8 v[82:85], v[170:173], v[194:197], v[82:85]
	v_mfma_i32_16x16x64_i8 v[66:69], v[178:181], v[194:197], v[66:69]
	v_mfma_i32_16x16x64_i8 v[94:97], v[170:173], v[202:205], v[94:97]
	v_mfma_i32_16x16x64_i8 v[78:81], v[178:181], v[202:205], v[78:81]
	v_mfma_i32_16x16x64_i8 v[90:93], v[170:173], v[210:213], v[90:93]
	v_mfma_i32_16x16x64_i8 v[74:77], v[178:181], v[210:213], v[74:77]
	v_mfma_i32_16x16x64_i8 v[86:89], v[174:177], v[190:193], v[86:89]
	v_mfma_i32_16x16x64_i8 v[70:73], v[182:185], v[190:193], v[70:73]
	v_mfma_i32_16x16x64_i8 v[82:85], v[174:177], v[198:201], v[82:85]
	v_mfma_i32_16x16x64_i8 v[66:69], v[182:185], v[198:201], v[66:69]
	v_mfma_i32_16x16x64_i8 v[94:97], v[174:177], v[206:209], v[94:97]
	v_mfma_i32_16x16x64_i8 v[78:81], v[182:185], v[206:209], v[78:81]
	v_mfma_i32_16x16x64_i8 v[90:93], v[174:177], v[214:217], v[90:93]
	v_mfma_i32_16x16x64_i8 v[74:77], v[182:185], v[214:217], v[74:77]
	s_barrier
	s_add_i32 s2, s94, s47
	v_lshl_add_u64 v[218:219], v[218:219], 0, s[14:15]
	s_mov_b32 m0, s2
	ds_read_b128 v[186:189], v236 offset:49152
	ds_read_b128 v[190:193], v236 offset:50176
	ds_read_b128 v[194:197], v236 offset:51200
	ds_read_b128 v[198:201], v236 offset:52224
	ds_read_b128 v[202:205], v236 offset:53248
	ds_read_b128 v[206:209], v236 offset:54272
	ds_read_b128 v[210:213], v236 offset:55296
	ds_read_b128 v[214:217], v236 offset:56320
	global_load_lds_dwordx4 v[218:219], off
	s_add_i32 m0, s2, 0x2000
	s_add_u32 s2, s18, 0x80080
	v_lshl_add_u64 v[218:219], v[220:221], 0, s[14:15]
	s_addc_u32 s3, s19, 0
	s_add_i32 s18, s95, s47
	global_load_lds_dwordx4 v[218:219], off
	v_lshl_add_u64 v[218:219], s[2:3], 0, v[144:145]
	s_mov_b32 m0, s18
	s_nop 0
	global_load_lds_dwordx4 v[218:219], off
	v_lshl_add_u64 v[218:219], s[2:3], 0, v[148:149]
	s_add_i32 m0, s18, 0x2000
	s_nop 0
	global_load_lds_dwordx4 v[218:219], off
	v_lshl_add_u64 v[218:219], v[222:223], 0, s[14:15]
	s_mov_b32 m0, s63
	s_nop 0
	global_load_lds_dwordx4 v[218:219], off
	v_lshl_add_u64 v[218:219], v[224:225], 0, s[14:15]
	s_mov_b32 m0, s64
	s_nop 0
	global_load_lds_dwordx4 v[218:219], off
	s_waitcnt vmcnt(8)
	s_waitcnt lgkmcnt(0)
	s_barrier
	s_waitcnt lgkmcnt(0)
	v_mfma_i32_16x16x64_i8 v[54:57], v[130:133], v[186:189], v[54:57]
	v_mfma_i32_16x16x64_i8 v[18:21], v[162:165], v[186:189], v[18:21]
	v_mfma_i32_16x16x64_i8 v[50:53], v[130:133], v[194:197], v[50:53]
	v_mfma_i32_16x16x64_i8 v[22:25], v[162:165], v[194:197], v[22:25]
	v_mfma_i32_16x16x64_i8 v[62:65], v[130:133], v[202:205], v[62:65]
	v_mfma_i32_16x16x64_i8 v[30:33], v[162:165], v[202:205], v[30:33]
	v_mfma_i32_16x16x64_i8 v[58:61], v[130:133], v[210:213], v[58:61]
	v_mfma_i32_16x16x64_i8 v[26:29], v[162:165], v[210:213], v[26:29]
	v_mfma_i32_16x16x64_i8 v[54:57], v[134:137], v[190:193], v[54:57]
	v_mfma_i32_16x16x64_i8 v[18:21], v[166:169], v[190:193], v[18:21]
	v_mfma_i32_16x16x64_i8 v[50:53], v[134:137], v[198:201], v[50:53]
	v_mfma_i32_16x16x64_i8 v[22:25], v[166:169], v[198:201], v[22:25]
	v_mfma_i32_16x16x64_i8 v[62:65], v[134:137], v[206:209], v[62:65]
	v_mfma_i32_16x16x64_i8 v[30:33], v[166:169], v[206:209], v[30:33]
	v_mfma_i32_16x16x64_i8 v[58:61], v[134:137], v[214:217], v[58:61]
	v_mfma_i32_16x16x64_i8 v[26:29], v[166:169], v[214:217], v[26:29]
	v_mfma_i32_16x16x64_i8 v[46:49], v[170:173], v[186:189], v[46:49]
	v_mfma_i32_16x16x64_i8 v[14:17], v[178:181], v[186:189], v[14:17]
	v_mfma_i32_16x16x64_i8 v[42:45], v[170:173], v[194:197], v[42:45]
	v_mfma_i32_16x16x64_i8 v[10:13], v[178:181], v[194:197], v[10:13]
	v_mfma_i32_16x16x64_i8 v[38:41], v[170:173], v[202:205], v[38:41]
	v_mfma_i32_16x16x64_i8 v[6:9], v[178:181], v[202:205], v[6:9]
	v_mfma_i32_16x16x64_i8 v[34:37], v[170:173], v[210:213], v[34:37]
	v_mfma_i32_16x16x64_i8 v[2:5], v[178:181], v[210:213], v[2:5]
	v_mfma_i32_16x16x64_i8 v[46:49], v[174:177], v[190:193], v[46:49]
	v_mfma_i32_16x16x64_i8 v[14:17], v[182:185], v[190:193], v[14:17]
	v_mfma_i32_16x16x64_i8 v[42:45], v[174:177], v[198:201], v[42:45]
	v_mfma_i32_16x16x64_i8 v[10:13], v[182:185], v[198:201], v[10:13]
	v_mfma_i32_16x16x64_i8 v[38:41], v[174:177], v[206:209], v[38:41]
	v_mfma_i32_16x16x64_i8 v[6:9], v[182:185], v[206:209], v[6:9]
	v_mfma_i32_16x16x64_i8 v[34:37], v[174:177], v[214:217], v[34:37]
	v_mfma_i32_16x16x64_i8 v[2:5], v[182:185], v[214:217], v[2:5]
	s_barrier
	s_add_i32 s93, s93, 2
	s_add_u32 s91, s91, 0x100
	s_addc_u32 s92, s92, 0
	s_cmp_gt_u32 s93, 29
	s_mov_b64 s[2:3], s[4:5]

.LBB0_2240:
	s_add_u32 s69, s36, 0x100
	s_addc_u32 s70, s37, 0
	s_mov_b32 s71, -2
	ds_read_b128 v[130:133], v212
	ds_read_b128 v[134:137], v212 offset:1024
	ds_read_b128 v[138:141], v212 offset:2048
	ds_read_b128 v[142:145], v212 offset:3072
	ds_read_b128 v[146:149], v213
	ds_read_b128 v[150:153], v213 offset:1024
	ds_read_b128 v[154:157], v213 offset:2048
	ds_read_b128 v[158:161], v213 offset:3072
	s_add_u32 s36, s18, 0x100
	s_addc_u32 s37, s19, 0
	s_cmpk_eq_i32 s71, 0xdc
	s_cselect_b32 s41, s3, s37
	s_cselect_b32 s40, s2, s36
	s_cselect_b32 s39, s35, s70
	s_cselect_b32 s38, s34, s69
	v_lshl_add_u64 v[216:217], s[18:19], 0, v[178:179]
	s_add_i32 m0, s44, 0xc000
	ds_read_b128 v[162:165], v214
	ds_read_b128 v[166:169], v214 offset:1024
	ds_read_b128 v[186:189], v214 offset:2048
	ds_read_b128 v[190:193], v214 offset:3072
	ds_read_b128 v[194:197], v214 offset:4096
	ds_read_b128 v[198:201], v214 offset:5120
	ds_read_b128 v[202:205], v214 offset:6144
	ds_read_b128 v[206:209], v214 offset:7168
	global_load_lds_dwordx4 v[216:217], off
	v_lshl_add_u64 v[216:217], s[18:19], 0, v[180:181]
	s_add_i32 m0, s44, 0xe000
	s_nop 0
	global_load_lds_dwordx4 v[216:217], off
	s_waitcnt vmcnt(8)
	s_waitcnt lgkmcnt(0)
	s_barrier
	s_waitcnt lgkmcnt(0)
	v_mfma_f32_16x16x32_bf16 v[126:129], v[130:133], v[162:165], 0
	v_mfma_f32_16x16x32_bf16 v[122:125], v[138:141], v[162:165], 0
	v_mfma_f32_16x16x32_bf16 v[110:113], v[130:133], v[186:189], 0
	v_mfma_f32_16x16x32_bf16 v[106:109], v[138:141], v[186:189], 0
	v_mfma_f32_16x16x32_bf16 v[94:97], v[130:133], v[194:197], 0
	v_mfma_f32_16x16x32_bf16 v[90:93], v[138:141], v[194:197], 0
	v_mfma_f32_16x16x32_bf16 v[78:81], v[130:133], v[202:205], 0
	v_mfma_f32_16x16x32_bf16 v[74:77], v[138:141], v[202:205], 0
	v_mfma_f32_16x16x32_bf16 v[126:129], v[134:137], v[166:169], v[126:129]
	v_mfma_f32_16x16x32_bf16 v[122:125], v[142:145], v[166:169], v[122:125]
	v_mfma_f32_16x16x32_bf16 v[110:113], v[134:137], v[190:193], v[110:113]
	v_mfma_f32_16x16x32_bf16 v[106:109], v[142:145], v[190:193], v[106:109]
	v_mfma_f32_16x16x32_bf16 v[94:97], v[134:137], v[198:201], v[94:97]
	v_mfma_f32_16x16x32_bf16 v[90:93], v[142:145], v[198:201], v[90:93]
	v_mfma_f32_16x16x32_bf16 v[78:81], v[134:137], v[206:209], v[78:81]
	v_mfma_f32_16x16x32_bf16 v[74:77], v[142:145], v[206:209], v[74:77]
	v_mfma_f32_16x16x32_bf16 v[118:121], v[146:149], v[162:165], 0
	v_mfma_f32_16x16x32_bf16 v[114:117], v[154:157], v[162:165], 0
	v_mfma_f32_16x16x32_bf16 v[102:105], v[146:149], v[186:189], 0
	v_mfma_f32_16x16x32_bf16 v[98:101], v[154:157], v[186:189], 0
	v_mfma_f32_16x16x32_bf16 v[86:89], v[146:149], v[194:197], 0
	v_mfma_f32_16x16x32_bf16 v[82:85], v[154:157], v[194:197], 0
	v_mfma_f32_16x16x32_bf16 v[70:73], v[146:149], v[202:205], 0
	v_mfma_f32_16x16x32_bf16 v[66:69], v[154:157], v[202:205], 0
	v_mfma_f32_16x16x32_bf16 v[118:121], v[150:153], v[166:169], v[118:121]
	v_mfma_f32_16x16x32_bf16 v[114:117], v[158:161], v[166:169], v[114:117]
	v_mfma_f32_16x16x32_bf16 v[102:105], v[150:153], v[190:193], v[102:105]
	v_mfma_f32_16x16x32_bf16 v[98:101], v[158:161], v[190:193], v[98:101]
	v_mfma_f32_16x16x32_bf16 v[86:89], v[150:153], v[198:201], v[86:89]
	v_mfma_f32_16x16x32_bf16 v[82:85], v[158:161], v[198:201], v[82:85]
	v_mfma_f32_16x16x32_bf16 v[70:73], v[150:153], v[206:209], v[70:73]
	v_mfma_f32_16x16x32_bf16 v[66:69], v[158:161], v[206:209], v[66:69]
	s_barrier
	s_add_i32 s18, s56, s43
	v_lshl_add_u64 v[216:217], s[38:39], 0, v[172:173]
	s_mov_b32 m0, s18
	ds_read_b128 v[162:165], v214 offset:16384
	ds_read_b128 v[166:169], v214 offset:17408
	ds_read_b128 v[186:189], v214 offset:18432
	ds_read_b128 v[190:193], v214 offset:19456
	ds_read_b128 v[194:197], v214 offset:20480
	ds_read_b128 v[198:201], v214 offset:21504
	ds_read_b128 v[202:205], v214 offset:22528
	ds_read_b128 v[206:209], v214 offset:23552
	global_load_lds_dwordx4 v[216:217], off
	s_add_i32 m0, s18, 0x2000
	s_add_u32 s18, s38, 0x380000
	v_lshl_add_u64 v[218:219], s[38:39], 0, v[176:177]
	s_addc_u32 s19, s39, 0
	s_add_i32 s72, s57, s43
	global_load_lds_dwordx4 v[218:219], off
	v_lshl_add_u64 v[220:221], s[18:19], 0, v[172:173]
	s_mov_b32 m0, s72
	v_lshl_add_u64 v[222:223], s[40:41], 0, v[174:175]
	global_load_lds_dwordx4 v[220:221], off
	v_lshl_add_u64 v[220:221], s[18:19], 0, v[176:177]
	s_add_i32 m0, s72, 0x2000
	s_nop 0
	global_load_lds_dwordx4 v[220:221], off
	v_lshl_add_u64 v[220:221], s[40:41], 0, v[170:171]
	s_mov_b32 m0, s44
	s_nop 0
	global_load_lds_dwordx4 v[220:221], off
	s_mov_b32 m0, s45
	s_nop 0
	global_load_lds_dwordx4 v[222:223], off
	s_waitcnt vmcnt(8)
	s_waitcnt lgkmcnt(0)
	s_barrier
	s_waitcnt lgkmcnt(0)
	v_mfma_f32_16x16x32_bf16 v[62:65], v[130:133], v[162:165], 0
	v_mfma_f32_16x16x32_bf16 v[58:61], v[138:141], v[162:165], 0
	v_mfma_f32_16x16x32_bf16 v[46:49], v[130:133], v[186:189], 0
	v_mfma_f32_16x16x32_bf16 v[42:45], v[138:141], v[186:189], 0
	v_mfma_f32_16x16x32_bf16 v[30:33], v[130:133], v[194:197], 0
	v_mfma_f32_16x16x32_bf16 v[26:29], v[138:141], v[194:197], 0
	v_mfma_f32_16x16x32_bf16 v[14:17], v[130:133], v[202:205], 0
	v_mfma_f32_16x16x32_bf16 v[10:13], v[138:141], v[202:205], 0
	v_mfma_f32_16x16x32_bf16 v[62:65], v[134:137], v[166:169], v[62:65]
	v_mfma_f32_16x16x32_bf16 v[58:61], v[142:145], v[166:169], v[58:61]
	v_mfma_f32_16x16x32_bf16 v[46:49], v[134:137], v[190:193], v[46:49]
	v_mfma_f32_16x16x32_bf16 v[42:45], v[142:145], v[190:193], v[42:45]
	v_mfma_f32_16x16x32_bf16 v[30:33], v[134:137], v[198:201], v[30:33]
	v_mfma_f32_16x16x32_bf16 v[26:29], v[142:145], v[198:201], v[26:29]
	v_mfma_f32_16x16x32_bf16 v[14:17], v[134:137], v[206:209], v[14:17]
	v_mfma_f32_16x16x32_bf16 v[10:13], v[142:145], v[206:209], v[10:13]
	v_mfma_f32_16x16x32_bf16 v[54:57], v[146:149], v[162:165], 0
	v_mfma_f32_16x16x32_bf16 v[50:53], v[154:157], v[162:165], 0
	v_mfma_f32_16x16x32_bf16 v[38:41], v[146:149], v[186:189], 0
	v_mfma_f32_16x16x32_bf16 v[34:37], v[154:157], v[186:189], 0
	v_mfma_f32_16x16x32_bf16 v[22:25], v[146:149], v[194:197], 0
	v_mfma_f32_16x16x32_bf16 v[18:21], v[154:157], v[194:197], 0
	v_mfma_f32_16x16x32_bf16 v[6:9], v[146:149], v[202:205], 0
	v_mfma_f32_16x16x32_bf16 v[2:5], v[154:157], v[202:205], 0
	v_mfma_f32_16x16x32_bf16 v[54:57], v[150:153], v[166:169], v[54:57]
	v_mfma_f32_16x16x32_bf16 v[50:53], v[158:161], v[166:169], v[50:53]
	v_mfma_f32_16x16x32_bf16 v[38:41], v[150:153], v[190:193], v[38:41]
	v_mfma_f32_16x16x32_bf16 v[34:37], v[158:161], v[190:193], v[34:37]
	v_mfma_f32_16x16x32_bf16 v[22:25], v[150:153], v[198:201], v[22:25]
	v_mfma_f32_16x16x32_bf16 v[18:21], v[158:161], v[198:201], v[18:21]
	v_mfma_f32_16x16x32_bf16 v[6:9], v[150:153], v[206:209], v[6:9]
	v_mfma_f32_16x16x32_bf16 v[2:5], v[158:161], v[206:209], v[2:5]
	s_barrier
	s_add_i32 s72, 0, 0x18000
	s_add_i32 s73, 0, 0x1c000
	v_add_u32_e32 v142, s72, v211
	v_add_u32_e32 v158, s73, v211
	ds_read_b128 v[130:133], v142
	ds_read_b128 v[134:137], v142 offset:1024
	ds_read_b128 v[138:141], v142 offset:2048
	ds_read_b128 v[142:145], v142 offset:3072
	ds_read_b128 v[146:149], v158
	ds_read_b128 v[150:153], v158 offset:1024
	ds_read_b128 v[154:157], v158 offset:2048
	ds_read_b128 v[158:161], v158 offset:3072
	s_add_u32 s18, s40, 0x380000
	s_addc_u32 s19, s41, 0
	s_mov_b32 m0, s46
	v_lshl_add_u64 v[224:225], s[18:19], 0, v[170:171]
	ds_read_b128 v[162:165], v214 offset:32768
	ds_read_b128 v[166:169], v214 offset:33792
	ds_read_b128 v[186:189], v214 offset:34816
	ds_read_b128 v[190:193], v214 offset:35840
	ds_read_b128 v[194:197], v214 offset:36864
	ds_read_b128 v[198:201], v214 offset:37888
	ds_read_b128 v[202:205], v214 offset:38912
	ds_read_b128 v[206:209], v214 offset:39936
	global_load_lds_dwordx4 v[224:225], off
	v_lshl_add_u64 v[224:225], s[18:19], 0, v[174:175]
	s_mov_b32 m0, s47
	s_nop 0
	global_load_lds_dwordx4 v[224:225], off
	s_waitcnt vmcnt(8)
	s_waitcnt lgkmcnt(0)
	s_barrier
	s_waitcnt lgkmcnt(0)
	v_mfma_f32_16x16x32_bf16 v[126:129], v[130:133], v[162:165], v[126:129]
	v_mfma_f32_16x16x32_bf16 v[122:125], v[138:141], v[162:165], v[122:125]
	v_mfma_f32_16x16x32_bf16 v[110:113], v[130:133], v[186:189], v[110:113]
	v_mfma_f32_16x16x32_bf16 v[106:109], v[138:141], v[186:189], v[106:109]
	v_mfma_f32_16x16x32_bf16 v[94:97], v[130:133], v[194:197], v[94:97]
	v_mfma_f32_16x16x32_bf16 v[90:93], v[138:141], v[194:197], v[90:93]
	v_mfma_f32_16x16x32_bf16 v[78:81], v[130:133], v[202:205], v[78:81]
	v_mfma_f32_16x16x32_bf16 v[74:77], v[138:141], v[202:205], v[74:77]
	v_mfma_f32_16x16x32_bf16 v[126:129], v[134:137], v[166:169], v[126:129]
	v_mfma_f32_16x16x32_bf16 v[122:125], v[142:145], v[166:169], v[122:125]
	v_mfma_f32_16x16x32_bf16 v[110:113], v[134:137], v[190:193], v[110:113]
	v_mfma_f32_16x16x32_bf16 v[106:109], v[142:145], v[190:193], v[106:109]
	v_mfma_f32_16x16x32_bf16 v[94:97], v[134:137], v[198:201], v[94:97]
	v_mfma_f32_16x16x32_bf16 v[90:93], v[142:145], v[198:201], v[90:93]
	v_mfma_f32_16x16x32_bf16 v[78:81], v[134:137], v[206:209], v[78:81]
	v_mfma_f32_16x16x32_bf16 v[74:77], v[142:145], v[206:209], v[74:77]
	v_mfma_f32_16x16x32_bf16 v[118:121], v[146:149], v[162:165], v[118:121]
	v_mfma_f32_16x16x32_bf16 v[114:117], v[154:157], v[162:165], v[114:117]
	v_mfma_f32_16x16x32_bf16 v[102:105], v[146:149], v[186:189], v[102:105]
	v_mfma_f32_16x16x32_bf16 v[98:101], v[154:157], v[186:189], v[98:101]
	v_mfma_f32_16x16x32_bf16 v[86:89], v[146:149], v[194:197], v[86:89]
	v_mfma_f32_16x16x32_bf16 v[82:85], v[154:157], v[194:197], v[82:85]
	v_mfma_f32_16x16x32_bf16 v[70:73], v[146:149], v[202:205], v[70:73]
	v_mfma_f32_16x16x32_bf16 v[66:69], v[154:157], v[202:205], v[66:69]
	v_mfma_f32_16x16x32_bf16 v[118:121], v[150:153], v[166:169], v[118:121]
	v_mfma_f32_16x16x32_bf16 v[114:117], v[158:161], v[166:169], v[114:117]
	v_mfma_f32_16x16x32_bf16 v[102:105], v[150:153], v[190:193], v[102:105]
	v_mfma_f32_16x16x32_bf16 v[98:101], v[158:161], v[190:193], v[98:101]
	v_mfma_f32_16x16x32_bf16 v[86:89], v[150:153], v[198:201], v[86:89]
	v_mfma_f32_16x16x32_bf16 v[82:85], v[158:161], v[198:201], v[82:85]
	v_mfma_f32_16x16x32_bf16 v[70:73], v[150:153], v[206:209], v[70:73]
	v_mfma_f32_16x16x32_bf16 v[66:69], v[158:161], v[206:209], v[66:69]
	s_barrier
	s_add_i32 s18, s72, s43
	v_lshl_add_u64 v[216:217], v[216:217], 0, s[8:9]
	s_mov_b32 m0, s18
	ds_read_b128 v[162:165], v214 offset:49152
	ds_read_b128 v[166:169], v214 offset:50176
	ds_read_b128 v[186:189], v214 offset:51200
	ds_read_b128 v[190:193], v214 offset:52224
	ds_read_b128 v[194:197], v214 offset:53248
	ds_read_b128 v[198:201], v214 offset:54272
	ds_read_b128 v[202:205], v214 offset:55296
	ds_read_b128 v[206:209], v214 offset:56320
	global_load_lds_dwordx4 v[216:217], off
	s_add_i32 m0, s18, 0x2000
	s_add_u32 s18, s38, 0x380080
	v_lshl_add_u64 v[216:217], v[218:219], 0, s[8:9]
	s_addc_u32 s19, s39, 0
	s_add_i32 s38, s73, s43
	global_load_lds_dwordx4 v[216:217], off
	v_lshl_add_u64 v[216:217], s[18:19], 0, v[172:173]
	s_mov_b32 m0, s38
	s_nop 0
	global_load_lds_dwordx4 v[216:217], off
	v_lshl_add_u64 v[216:217], s[18:19], 0, v[176:177]
	s_add_i32 m0, s38, 0x2000
	s_nop 0
	global_load_lds_dwordx4 v[216:217], off
	v_lshl_add_u64 v[216:217], v[220:221], 0, s[8:9]
	s_mov_b32 m0, s51
	s_nop 0
	global_load_lds_dwordx4 v[216:217], off
	v_lshl_add_u64 v[216:217], v[222:223], 0, s[8:9]
	s_mov_b32 m0, s54
	s_nop 0
	global_load_lds_dwordx4 v[216:217], off
	s_waitcnt vmcnt(8)
	s_waitcnt lgkmcnt(0)
	s_barrier
	s_waitcnt lgkmcnt(0)
	v_mfma_f32_16x16x32_bf16 v[62:65], v[130:133], v[162:165], v[62:65]
	v_mfma_f32_16x16x32_bf16 v[58:61], v[138:141], v[162:165], v[58:61]
	v_mfma_f32_16x16x32_bf16 v[46:49], v[130:133], v[186:189], v[46:49]
	v_mfma_f32_16x16x32_bf16 v[42:45], v[138:141], v[186:189], v[42:45]
	v_mfma_f32_16x16x32_bf16 v[30:33], v[130:133], v[194:197], v[30:33]
	v_mfma_f32_16x16x32_bf16 v[26:29], v[138:141], v[194:197], v[26:29]
	v_mfma_f32_16x16x32_bf16 v[14:17], v[130:133], v[202:205], v[14:17]
	v_mfma_f32_16x16x32_bf16 v[10:13], v[138:141], v[202:205], v[10:13]
	v_mfma_f32_16x16x32_bf16 v[62:65], v[134:137], v[166:169], v[62:65]
	v_mfma_f32_16x16x32_bf16 v[58:61], v[142:145], v[166:169], v[58:61]
	v_mfma_f32_16x16x32_bf16 v[46:49], v[134:137], v[190:193], v[46:49]
	v_mfma_f32_16x16x32_bf16 v[42:45], v[142:145], v[190:193], v[42:45]
	v_mfma_f32_16x16x32_bf16 v[30:33], v[134:137], v[198:201], v[30:33]
	v_mfma_f32_16x16x32_bf16 v[26:29], v[142:145], v[198:201], v[26:29]
	v_mfma_f32_16x16x32_bf16 v[14:17], v[134:137], v[206:209], v[14:17]
	v_mfma_f32_16x16x32_bf16 v[10:13], v[142:145], v[206:209], v[10:13]
	v_mfma_f32_16x16x32_bf16 v[54:57], v[146:149], v[162:165], v[54:57]
	v_mfma_f32_16x16x32_bf16 v[50:53], v[154:157], v[162:165], v[50:53]
	v_mfma_f32_16x16x32_bf16 v[38:41], v[146:149], v[186:189], v[38:41]
	v_mfma_f32_16x16x32_bf16 v[34:37], v[154:157], v[186:189], v[34:37]
	v_mfma_f32_16x16x32_bf16 v[22:25], v[146:149], v[194:197], v[22:25]
	v_mfma_f32_16x16x32_bf16 v[18:21], v[154:157], v[194:197], v[18:21]
	v_mfma_f32_16x16x32_bf16 v[6:9], v[146:149], v[202:205], v[6:9]
	v_mfma_f32_16x16x32_bf16 v[2:5], v[154:157], v[202:205], v[2:5]
	v_mfma_f32_16x16x32_bf16 v[54:57], v[150:153], v[166:169], v[54:57]
	v_mfma_f32_16x16x32_bf16 v[50:53], v[158:161], v[166:169], v[50:53]
	v_mfma_f32_16x16x32_bf16 v[38:41], v[150:153], v[190:193], v[38:41]
	v_mfma_f32_16x16x32_bf16 v[34:37], v[158:161], v[190:193], v[34:37]
	v_mfma_f32_16x16x32_bf16 v[22:25], v[150:153], v[198:201], v[22:25]
	v_mfma_f32_16x16x32_bf16 v[18:21], v[158:161], v[198:201], v[18:21]
	v_mfma_f32_16x16x32_bf16 v[6:9], v[150:153], v[206:209], v[6:9]
	v_mfma_f32_16x16x32_bf16 v[2:5], v[158:161], v[206:209], v[2:5]
	s_barrier
	s_add_i32 s71, s71, 2
	s_add_u32 s69, s69, 0x100
	s_addc_u32 s70, s70, 0
	s_cmpk_gt_u32 s71, 0xdd
	s_mov_b64 s[18:19], s[36:37]
